# wave sums via DPP/permlane swap in rms loops; sample item first wait counted
# baseline (speedup 1.0000x reference)
.LBB0_47:
	v_lshl_add_u64 v[22:23], v[82:83], 4, s[18:19]
	global_load_dwordx4 v[78:81], v[22:23], off
	global_load_dwordx4 v[74:77], v[22:23], off offset:1024
	global_load_dwordx4 v[62:65], v[22:23], off offset:3072
	global_load_dwordx4 v[70:73], v[22:23], off offset:2048
	s_mov_b64 s[18:19], 0x1000
	v_lshl_add_u64 v[2:3], v[22:23], 0, s[18:19]
	global_load_dwordx4 v[54:57], v[2:3], off offset:1024
	global_load_dwordx4 v[50:53], v[2:3], off offset:2048
	global_load_dwordx4 v[46:49], v[2:3], off offset:3072
	v_add_co_u32_e32 v2, vcc, 0x1000, v22
	s_lshl_b64 s[0:1], s[0:1], 11
	s_nop 0
	v_addc_co_u32_e32 v3, vcc, 0, v23, vcc
	global_load_dwordx4 v[66:69], v[2:3], off
	global_load_dwordx4 v[14:17], v[86:87], off
	global_load_dwordx4 v[10:13], v[86:87], off offset:1024
	global_load_dwordx4 v[6:9], v[86:87], off offset:2048
	s_nop 0
	global_load_dwordx4 v[2:5], v[86:87], off offset:3072
	s_mov_b64 s[18:19], 0x2000
	v_add_co_u32_e32 v32, vcc, 0x2000, v22
	v_lshl_add_u64 v[24:25], v[22:23], 0, s[18:19]
	s_mov_b64 s[18:19], 0x3000
	v_lshl_add_u64 v[90:91], v[84:85], 0, s[0:1]
	s_mov_b64 s[0:1], vcc
	v_add_co_u32_e32 v98, vcc, 0x3000, v22
	v_lshl_add_u64 v[30:31], v[22:23], 0, s[18:19]
	v_addc_co_u32_e64 v33, s[0:1], 0, v23, s[0:1]
	v_addc_co_u32_e32 v99, vcc, 0, v23, vcc
	global_load_dwordx4 v[42:45], v[24:25], off offset:1024
	global_load_dwordx4 v[34:37], v[24:25], off offset:2048
	global_load_dwordx4 v[26:29], v[30:31], off offset:1024
	global_load_dwordx4 v[18:21], v[30:31], off offset:2048
	global_load_dwordx4 v[38:41], v[24:25], off offset:3072
	global_load_dwordx4 v[58:61], v[32:33], off
	s_nop 0
	global_load_dwordx4 v[22:25], v[30:31], off offset:3072
	s_nop 0
	global_load_dwordx4 v[30:33], v[98:99], off
	s_movk_i32 s0, 0xf000
	s_add_u32 s16, s16, s8
	s_addc_u32 s17, s17, s9
	s_add_u32 s10, s10, s12
	s_addc_u32 s11, s11, s13
	s_cmpk_lt_i32 s16, 0x4200
	s_waitcnt vmcnt(19)
	v_pk_mul_f32 v[98:99], v[80:81], v[80:81]
	v_pk_mul_f32 v[100:101], v[78:79], v[78:79]
	s_waitcnt vmcnt(18)
	v_pk_mul_f32 v[102:103], v[76:77], v[76:77]
	v_pk_mul_f32 v[104:105], v[74:75], v[74:75]
	v_pk_mov_b32 v[110:111], v[100:101], v[98:99] op_sel:[1,0]
	v_mov_b32_e32 v101, v99
	v_pk_mov_b32 v[98:99], v[104:105], v[102:103] op_sel:[1,0]
	v_mov_b32_e32 v105, v103
	s_waitcnt vmcnt(16)
	v_mul_f32_e32 v106, v71, v71
	v_mul_f32_e32 v108, v73, v73
	v_pk_add_f32 v[100:101], v[110:111], v[100:101]
	v_pk_add_f32 v[98:99], v[98:99], v[104:105]
	v_mul_f32_e32 v114, v62, v62
	v_mul_f32_e32 v115, v63, v63
	v_mul_f32_e32 v116, v64, v64
	v_mul_f32_e32 v117, v65, v65
	v_pk_fma_f32 v[102:103], v[70:71], v[70:71], v[106:107] op_sel_hi:[1,1,0]
	v_pk_fma_f32 v[106:107], v[72:73], v[72:73], v[108:109] op_sel_hi:[1,1,0]
	v_pk_add_f32 v[100:101], v[100:101], v[100:101] op_sel:[0,1] op_sel_hi:[1,0]
	v_pk_add_f32 v[98:99], v[98:99], v[98:99] op_sel:[0,1] op_sel_hi:[1,0]
	v_mov_b32_e32 v103, v116
	v_mov_b32_e32 v107, v117
	v_mov_b32_e32 v101, v114
	v_mov_b32_e32 v99, v115
	v_pk_add_f32 v[102:103], v[102:103], v[106:107]
	v_pk_add_f32 v[98:99], v[100:101], v[98:99]
	s_waitcnt vmcnt(15)
	v_pk_mul_f32 v[108:109], v[56:57], v[56:57]
	v_pk_add_f32 v[98:99], v[98:99], v[102:103]
	v_pk_mul_f32 v[112:113], v[54:55], v[54:55]
	v_add_f32_e32 v99, v98, v99
	v_pk_mov_b32 v[102:103], v[112:113], v[108:109] op_sel:[1,0]
	v_mov_b32_e32 v113, v109
	s_waitcnt vmcnt(12)
	v_pk_mul_f32 v[104:105], v[68:69], v[68:69]
	v_pk_mul_f32 v[106:107], v[66:67], v[66:67]
	s_waitcnt lgkmcnt(0)
	s_nop 1
	v_add_f32_dpp v99, v99, v99 quad_perm:[1,0,3,2] row_mask:0xf bank_mask:0xf
	v_pk_add_f32 v[102:103], v[102:103], v[112:113]
	v_mul_f32_e32 v98, v51, v51
	v_mul_f32_e32 v100, v53, v53
	v_mul_f32_e32 v114, v48, v48
	s_waitcnt lgkmcnt(0)
	s_nop 1
	v_add_f32_dpp v108, v99, v99 quad_perm:[2,3,0,1] row_mask:0xf bank_mask:0xf
	v_mul_f32_e32 v115, v49, v49
	v_pk_fma_f32 v[98:99], v[50:51], v[50:51], v[98:99] op_sel_hi:[1,1,0]
	v_pk_fma_f32 v[100:101], v[52:53], v[52:53], v[100:101] op_sel_hi:[1,1,0]
	v_mov_b32_e32 v99, v114
	s_waitcnt lgkmcnt(0)
	s_nop 1
	v_add_f32_dpp v116, v108, v108 row_half_mirror row_mask:0xf bank_mask:0xf
	v_pk_mov_b32 v[108:109], v[106:107], v[104:105] op_sel:[1,0]
	v_mov_b32_e32 v107, v105
	v_mov_b32_e32 v101, v115
	v_pk_add_f32 v[98:99], v[98:99], v[100:101]
	s_waitcnt lgkmcnt(0)
	s_nop 1
	v_add_f32_dpp v104, v116, v116 row_mirror row_mask:0xf bank_mask:0xf
	v_mov_b32_e32 v112, v104
	v_pk_add_f32 v[100:101], v[108:109], v[106:107]
	v_mul_f32_e32 v110, v46, v46
	v_mul_f32_e32 v111, v47, v47
	v_pk_add_f32 v[102:103], v[102:103], v[102:103] op_sel:[0,1] op_sel_hi:[1,0]
	s_waitcnt lgkmcnt(0)
	s_nop 1
	v_permlane16_swap_b32_e32 v112, v104
	v_add_f32_e32 v104, v104, v112
	v_mov_b32_e32 v105, v104
	v_pk_add_f32 v[100:101], v[100:101], v[100:101] op_sel:[0,1] op_sel_hi:[1,0]
	v_mov_b32_e32 v103, v111
	v_mov_b32_e32 v101, v110
	v_pk_add_f32 v[100:101], v[100:101], v[102:103]
	s_waitcnt lgkmcnt(0)
	s_nop 1
	v_permlane32_swap_b32_e32 v105, v104
	v_add_f32_e32 v102, v104, v105
	v_fmamk_f32 v102, v102, 0x3a800000, v97
	v_mul_f32_e32 v103, 0x4b800000, v102
	v_cmp_gt_f32_e32 vcc, s20, v102
	v_pk_add_f32 v[98:99], v[100:101], v[98:99]
	s_nop 0
	v_cndmask_b32_e32 v102, v102, v103, vcc
	v_rsq_f32_e32 v102, v102
	v_add_f32_e32 v98, v98, v99
	v_mul_f32_e32 v100, 0x45800000, v102
	v_cndmask_b32_e32 v100, v102, v100, vcc
	v_mul_f32_e32 v78, v78, v100
	v_mul_f32_e32 v79, v79, v100
	v_mul_f32_e32 v74, v74, v100
	v_mul_f32_e32 v80, v80, v100
	v_mul_f32_e32 v81, v81, v100
	v_mul_f32_e32 v75, v75, v100
	s_waitcnt vmcnt(11)
	v_mul_f32_e32 v78, v14, v78
	v_mul_f32_e32 v79, v15, v79
	s_waitcnt vmcnt(10)
	v_mul_f32_e32 v101, v10, v74
	v_cvt_pk_bf16_f32 v74, v78, v79
	v_mul_f32_e32 v80, v16, v80
	v_mul_f32_e32 v81, v17, v81
	v_mul_f32_e32 v102, v11, v75
	v_cvt_pk_bf16_f32 v75, v80, v81
	global_store_dwordx2 v[90:91], v[74:75], off
	s_waitcnt lgkmcnt(0)
	s_nop 1
	v_add_f32_dpp v74, v98, v98 quad_perm:[1,0,3,2] row_mask:0xf bank_mask:0xf
	v_mul_f32_e32 v70, v70, v100
	v_mul_f32_e32 v71, v71, v100
	s_waitcnt vmcnt(10)
	v_mul_f32_e32 v70, v6, v70
	v_mul_f32_e32 v71, v7, v71
	s_waitcnt lgkmcnt(0)
	s_nop 1
	v_add_f32_dpp v74, v74, v74 quad_perm:[2,3,0,1] row_mask:0xf bank_mask:0xf
	v_cvt_pk_bf16_f32 v70, v70, v71
	v_mul_f32_e32 v71, v72, v100
	v_mul_f32_e32 v71, v8, v71
	v_mul_f32_e32 v73, v73, v100
	s_waitcnt lgkmcnt(0)
	s_nop 1
	v_add_f32_dpp v72, v74, v74 row_half_mirror row_mask:0xf bank_mask:0xf
	v_mul_f32_e32 v73, v9, v73
	v_cvt_pk_bf16_f32 v71, v71, v73
	global_store_dwordx2 v[90:91], v[70:71], off offset:1024
	v_mul_f32_e32 v62, v62, v100
	s_waitcnt lgkmcnt(0)
	s_nop 1
	v_add_f32_dpp v70, v72, v72 row_mirror row_mask:0xf bank_mask:0xf
	v_mov_b32_e32 v71, v70
	v_mul_f32_e32 v63, v63, v100
	s_waitcnt vmcnt(10)
	v_mul_f32_e32 v62, v2, v62
	v_mul_f32_e32 v63, v3, v63
	v_cvt_pk_bf16_f32 v62, v62, v63
	s_waitcnt lgkmcnt(0)
	s_nop 1
	v_permlane16_swap_b32_e32 v71, v70
	v_add_f32_e32 v70, v70, v71
	v_mov_b32_e32 v71, v70
	v_mul_f32_e32 v63, v64, v100
	v_mul_f32_e32 v64, v65, v100
	v_mul_f32_e32 v63, v4, v63
	v_mul_f32_e32 v64, v5, v64
	s_waitcnt lgkmcnt(0)
	s_nop 1
	v_permlane32_swap_b32_e32 v71, v70
	v_add_f32_e32 v65, v70, v71
	v_fmamk_f32 v65, v65, 0x3a800000, v97
	v_mul_f32_e32 v70, 0x4b800000, v65
	v_cmp_gt_f32_e32 vcc, s20, v65
	v_cvt_pk_bf16_f32 v63, v63, v64
	global_store_dwordx2 v[90:91], v[62:63], off offset:1536
	v_mul_f32_e32 v77, v77, v100
	v_cndmask_b32_e32 v65, v65, v70, vcc
	v_rsq_f32_e32 v65, v65
	v_mul_f32_e32 v76, v76, v100
	v_mul_f32_e32 v77, v13, v77
	v_mul_f32_e32 v103, v12, v76
	v_mul_f32_e32 v62, 0x45800000, v65
	v_cndmask_b32_e32 v72, v65, v62, vcc
	v_mul_f32_e32 v62, v66, v72
	v_mul_f32_e32 v63, v67, v72
	v_mul_f32_e32 v62, v14, v62
	v_mul_f32_e32 v63, v15, v63
	v_cvt_pk_bf16_f32 v62, v62, v63
	v_mul_f32_e32 v63, v68, v72
	v_mul_f32_e32 v64, v69, v72
	v_mul_f32_e32 v63, v16, v63
	v_mul_f32_e32 v64, v17, v64
	v_cvt_pk_bf16_f32 v63, v63, v64
	v_add_co_u32_e32 v64, vcc, s0, v88
	v_cvt_pk_bf16_f32 v76, v101, v102
	v_cvt_pk_bf16_f32 v77, v103, v77
	global_store_dwordx2 v[90:91], v[76:77], off offset:512
	s_nop 0
	v_addc_co_u32_e32 v65, vcc, -1, v89, vcc
	global_store_dwordx2 v[64:65], v[62:63], off offset:-1536
	s_waitcnt vmcnt(7)
	v_pk_mul_f32 v[62:63], v[60:61], v[60:61]
	v_pk_mul_f32 v[66:67], v[58:59], v[58:59]
	v_mul_f32_e32 v54, v54, v72
	v_pk_mov_b32 v[68:69], v[66:67], v[62:63] op_sel:[1,0]
	v_mov_b32_e32 v67, v63
	v_pk_add_f32 v[62:63], v[68:69], v[66:67]
	v_pk_mul_f32 v[66:67], v[44:45], v[44:45]
	v_pk_mul_f32 v[68:69], v[42:43], v[42:43]
	v_mul_f32_e32 v55, v55, v72
	v_pk_mov_b32 v[70:71], v[68:69], v[66:67] op_sel:[1,0]
	v_mov_b32_e32 v69, v67
	v_mul_f32_e32 v54, v10, v54
	v_mul_f32_e32 v55, v11, v55
	v_pk_add_f32 v[66:67], v[70:71], v[68:69]
	v_cvt_pk_bf16_f32 v54, v54, v55
	v_mul_f32_e32 v55, v56, v72
	v_mul_f32_e32 v56, v38, v38
	v_mul_f32_e32 v68, v39, v39
	v_pk_add_f32 v[62:63], v[62:63], v[62:63] op_sel:[0,1] op_sel_hi:[1,0]
	v_pk_add_f32 v[66:67], v[66:67], v[66:67] op_sel:[0,1] op_sel_hi:[1,0]
	v_mov_b32_e32 v63, v56
	v_mov_b32_e32 v67, v68
	v_mul_f32_e32 v56, v35, v35
	v_mul_f32_e32 v69, v40, v40
	v_pk_add_f32 v[62:63], v[62:63], v[66:67]
	v_pk_fma_f32 v[66:67], v[34:35], v[34:35], v[56:57] op_sel_hi:[1,1,0]
	v_mul_f32_e32 v56, v37, v37
	v_mul_f32_e32 v70, v41, v41
	v_mov_b32_e32 v67, v69
	v_pk_fma_f32 v[68:69], v[36:37], v[36:37], v[56:57] op_sel_hi:[1,1,0]
	v_mul_f32_e32 v57, v57, v72
	v_mov_b32_e32 v69, v70
	v_pk_add_f32 v[66:67], v[66:67], v[68:69]
	v_mul_f32_e32 v55, v12, v55
	v_pk_add_f32 v[62:63], v[62:63], v[66:67]
	v_mul_f32_e32 v57, v13, v57
	v_add_f32_e32 v56, v62, v63
	v_cvt_pk_bf16_f32 v55, v55, v57
	global_store_dwordx2 v[64:65], v[54:55], off offset:-1024
	v_mul_f32_e32 v50, v50, v72
	v_mul_f32_e32 v51, v51, v72
	s_waitcnt lgkmcnt(0)
	s_nop 1
	v_add_f32_dpp v56, v56, v56 quad_perm:[1,0,3,2] row_mask:0xf bank_mask:0xf
	v_mul_f32_e32 v50, v6, v50
	v_mul_f32_e32 v51, v7, v51
	v_cvt_pk_bf16_f32 v50, v50, v51
	v_mul_f32_e32 v51, v52, v72
	s_waitcnt lgkmcnt(0)
	s_nop 1
	v_add_f32_dpp v54, v56, v56 quad_perm:[2,3,0,1] row_mask:0xf bank_mask:0xf
	v_mul_f32_e32 v51, v8, v51
	v_mul_f32_e32 v53, v53, v72
	v_mul_f32_e32 v53, v9, v53
	v_cvt_pk_bf16_f32 v51, v51, v53
	s_waitcnt lgkmcnt(0)
	s_nop 1
	v_add_f32_dpp v52, v54, v54 row_half_mirror row_mask:0xf bank_mask:0xf
	global_store_dwordx2 v[64:65], v[50:51], off offset:-512
	v_mul_f32_e32 v46, v46, v72
	v_mul_f32_e32 v47, v47, v72
	v_mul_f32_e32 v46, v2, v46
	s_waitcnt lgkmcnt(0)
	s_nop 1
	v_add_f32_dpp v50, v52, v52 row_mirror row_mask:0xf bank_mask:0xf
	v_mov_b32_e32 v51, v50
	v_mul_f32_e32 v47, v3, v47
	v_cvt_pk_bf16_f32 v46, v46, v47
	v_mul_f32_e32 v47, v48, v72
	v_mul_f32_e32 v48, v49, v72
	s_waitcnt lgkmcnt(0)
	s_nop 1
	v_permlane16_swap_b32_e32 v51, v50
	v_add_f32_e32 v50, v50, v51
	v_mov_b32_e32 v51, v50
	v_mul_f32_e32 v47, v4, v47
	v_mul_f32_e32 v48, v5, v48
	v_cvt_pk_bf16_f32 v47, v47, v48
	global_store_dwordx2 v[88:89], v[46:47], off offset:-4096
	s_waitcnt lgkmcnt(0)
	s_nop 1
	v_permlane32_swap_b32_e32 v51, v50
	v_add_f32_e32 v49, v50, v51
	v_fmamk_f32 v49, v49, 0x3a800000, v97
	v_mul_f32_e32 v50, 0x4b800000, v49
	v_cmp_gt_f32_e32 vcc, s20, v49
	s_nop 1
	v_cndmask_b32_e32 v49, v49, v50, vcc
	v_rsq_f32_e32 v49, v49
	s_nop 0
	v_mul_f32_e32 v46, 0x45800000, v49
	v_cndmask_b32_e32 v54, v49, v46, vcc
	v_mul_f32_e32 v46, v58, v54
	v_mul_f32_e32 v47, v59, v54
	v_mul_f32_e32 v46, v14, v46
	v_mul_f32_e32 v47, v15, v47
	v_cvt_pk_bf16_f32 v46, v46, v47
	v_mul_f32_e32 v47, v60, v54
	v_mul_f32_e32 v47, v16, v47
	v_mul_f32_e32 v48, v61, v54
	v_mul_f32_e32 v48, v17, v48
	v_cvt_pk_bf16_f32 v47, v47, v48
	global_store_dwordx2 v[88:89], v[46:47], off offset:-3584
	s_waitcnt vmcnt(9)
	v_pk_mul_f32 v[46:47], v[32:33], v[32:33]
	v_pk_mul_f32 v[48:49], v[30:31], v[30:31]
	v_mul_f32_e32 v42, v42, v54
	v_pk_mov_b32 v[50:51], v[48:49], v[46:47] op_sel:[1,0]
	v_mov_b32_e32 v49, v47
	v_pk_add_f32 v[46:47], v[50:51], v[48:49]
	v_pk_mul_f32 v[48:49], v[28:29], v[28:29]
	v_pk_mul_f32 v[50:51], v[26:27], v[26:27]
	v_mul_f32_e32 v43, v43, v54
	v_pk_mov_b32 v[52:53], v[50:51], v[48:49] op_sel:[1,0]
	v_mov_b32_e32 v51, v49
	v_mul_f32_e32 v42, v10, v42
	v_mul_f32_e32 v43, v11, v43
	v_pk_add_f32 v[48:49], v[52:53], v[50:51]
	v_cvt_pk_bf16_f32 v42, v42, v43
	v_mul_f32_e32 v43, v44, v54
	v_mul_f32_e32 v44, v22, v22
	v_mul_f32_e32 v50, v23, v23
	v_pk_add_f32 v[46:47], v[46:47], v[46:47] op_sel:[0,1] op_sel_hi:[1,0]
	v_pk_add_f32 v[48:49], v[48:49], v[48:49] op_sel:[0,1] op_sel_hi:[1,0]
	v_mov_b32_e32 v47, v44
	v_mov_b32_e32 v49, v50
	v_mul_f32_e32 v44, v19, v19
	v_mul_f32_e32 v51, v24, v24
	v_pk_add_f32 v[46:47], v[46:47], v[48:49]
	v_pk_fma_f32 v[48:49], v[18:19], v[18:19], v[44:45] op_sel_hi:[1,1,0]
	v_mul_f32_e32 v44, v21, v21
	v_mul_f32_e32 v52, v25, v25
	v_mov_b32_e32 v49, v51
	v_pk_fma_f32 v[50:51], v[20:21], v[20:21], v[44:45] op_sel_hi:[1,1,0]
	v_mul_f32_e32 v45, v45, v54
	v_mov_b32_e32 v51, v52
	v_pk_add_f32 v[48:49], v[48:49], v[50:51]
	v_mul_f32_e32 v43, v12, v43
	v_pk_add_f32 v[46:47], v[46:47], v[48:49]
	v_mul_f32_e32 v45, v13, v45
	v_add_f32_e32 v44, v46, v47
	v_cvt_pk_bf16_f32 v43, v43, v45
	global_store_dwordx2 v[88:89], v[42:43], off offset:-3072
	v_mul_f32_e32 v34, v34, v54
	v_mul_f32_e32 v35, v35, v54
	s_waitcnt lgkmcnt(0)
	s_nop 1
	v_add_f32_dpp v44, v44, v44 quad_perm:[1,0,3,2] row_mask:0xf bank_mask:0xf
	v_mul_f32_e32 v34, v6, v34
	v_mul_f32_e32 v35, v7, v35
	v_cvt_pk_bf16_f32 v34, v34, v35
	v_mul_f32_e32 v35, v36, v54
	s_waitcnt lgkmcnt(0)
	s_nop 1
	v_add_f32_dpp v42, v44, v44 quad_perm:[2,3,0,1] row_mask:0xf bank_mask:0xf
	v_mul_f32_e32 v35, v8, v35
	v_mul_f32_e32 v37, v37, v54
	v_mul_f32_e32 v37, v9, v37
	v_cvt_pk_bf16_f32 v35, v35, v37
	s_waitcnt lgkmcnt(0)
	s_nop 1
	v_add_f32_dpp v36, v42, v42 row_half_mirror row_mask:0xf bank_mask:0xf
	global_store_dwordx2 v[88:89], v[34:35], off offset:-2560
	v_mul_f32_e32 v37, v39, v54
	v_mul_f32_e32 v37, v3, v37
	s_waitcnt lgkmcnt(0)
	s_nop 1
	v_add_f32_dpp v34, v36, v36 row_mirror row_mask:0xf bank_mask:0xf
	v_mov_b32_e32 v35, v34
	v_mul_f32_e32 v36, v38, v54
	v_mul_f32_e32 v36, v2, v36
	s_waitcnt lgkmcnt(0)
	s_nop 1
	v_permlane16_swap_b32_e32 v35, v34
	v_add_f32_e32 v35, v34, v35
	v_mov_b32_e32 v38, v35
	v_cvt_pk_bf16_f32 v34, v36, v37
	v_mul_f32_e32 v37, v41, v54
	v_mul_f32_e32 v36, v40, v54
	v_mul_f32_e32 v36, v4, v36
	s_waitcnt lgkmcnt(0)
	s_nop 1
	v_permlane32_swap_b32_e32 v38, v35
	v_add_f32_e32 v35, v35, v38
	v_fmamk_f32 v35, v35, 0x3a800000, v97
	v_mul_f32_e32 v38, 0x4b800000, v35
	v_cmp_gt_f32_e32 vcc, s20, v35
	s_nop 1
	v_cndmask_b32_e32 v35, v35, v38, vcc
	v_rsq_f32_e32 v38, v35
	v_mul_f32_e32 v35, v5, v37
	v_cvt_pk_bf16_f32 v35, v36, v35
	global_store_dwordx2 v[88:89], v[34:35], off offset:-2048
	v_mul_f32_e32 v34, 0x45800000, v38
	v_cndmask_b32_e32 v34, v38, v34, vcc
	v_mul_f32_e32 v30, v30, v34
	v_mul_f32_e32 v14, v14, v30
	v_mul_f32_e32 v30, v31, v34
	v_mul_f32_e32 v15, v15, v30
	v_cvt_pk_bf16_f32 v14, v14, v15
	v_mul_f32_e32 v15, v32, v34
	v_mul_f32_e32 v15, v16, v15
	v_mul_f32_e32 v16, v33, v34
	v_mul_f32_e32 v16, v17, v16
	v_cvt_pk_bf16_f32 v15, v15, v16
	global_store_dwordx2 v[88:89], v[14:15], off offset:-1536
	v_mul_f32_e32 v14, v26, v34
	v_mul_f32_e32 v10, v10, v14
	v_mul_f32_e32 v14, v27, v34
	v_mul_f32_e32 v11, v11, v14
	v_cvt_pk_bf16_f32 v10, v10, v11
	v_mul_f32_e32 v11, v28, v34
	v_mul_f32_e32 v11, v12, v11
	v_mul_f32_e32 v12, v29, v34
	v_mul_f32_e32 v12, v13, v12
	v_cvt_pk_bf16_f32 v11, v11, v12
	global_store_dwordx2 v[88:89], v[10:11], off offset:-1024
	v_mul_f32_e32 v10, v18, v34
	v_mul_f32_e32 v6, v6, v10
	v_mul_f32_e32 v10, v19, v34
	v_mul_f32_e32 v7, v7, v10
	v_cvt_pk_bf16_f32 v6, v6, v7
	v_mul_f32_e32 v7, v20, v34
	v_mul_f32_e32 v7, v8, v7
	v_mul_f32_e32 v8, v21, v34
	v_mul_f32_e32 v8, v9, v8
	v_cvt_pk_bf16_f32 v7, v7, v8
	global_store_dwordx2 v[88:89], v[6:7], off offset:-512
	v_mul_f32_e32 v6, v22, v34
	v_mul_f32_e32 v2, v2, v6
	v_mul_f32_e32 v6, v23, v34
	v_mul_f32_e32 v3, v3, v6
	v_cvt_pk_bf16_f32 v2, v2, v3
	v_mul_f32_e32 v3, v24, v34
	v_mul_f32_e32 v3, v4, v3
	v_mul_f32_e32 v4, v25, v34
	v_mul_f32_e32 v4, v5, v4
	v_cvt_pk_bf16_f32 v3, v3, v4
	global_store_dwordx2 v[88:89], v[2:3], off
	v_lshl_add_u64 v[88:89], v[88:89], 0, s[14:15]
	s_cbranch_scc0 .LBB0_50

.LBB0_561:
	global_load_dwordx4 v[80:83], v[70:71], off
	global_load_dwordx4 v[84:87], v[70:71], off offset:1024
	global_load_dwordx4 v[88:91], v[70:71], off offset:2048
	global_load_dwordx4 v[92:95], v[70:71], off offset:3072
	v_add_co_u32_e32 v0, vcc, 0x1000, v70
	s_add_i32 s6, s6, s0
	s_nop 0
	v_addc_co_u32_e32 v1, vcc, 0, v71, vcc
	global_load_dwordx4 v[60:63], v[0:1], off
	global_load_dwordx4 v[56:59], v[0:1], off offset:1024
	global_load_dwordx4 v[52:55], v[0:1], off offset:2048
	global_load_dwordx4 v[48:51], v[0:1], off offset:3072
	v_add_co_u32_e32 v0, vcc, 0x2000, v70
	s_cmpk_gt_i32 s6, 0x3fff
	s_nop 0
	v_addc_co_u32_e32 v1, vcc, 0, v71, vcc
	global_load_dwordx4 v[44:47], v[0:1], off
	global_load_dwordx4 v[32:35], v[0:1], off offset:1024
	global_load_dwordx4 v[24:27], v[0:1], off offset:2048
	global_load_dwordx4 v[16:19], v[0:1], off offset:3072
	v_add_co_u32_e32 v0, vcc, 0x3000, v70
	v_addc_co_u32_e32 v1, vcc, 0, v71, vcc
	global_load_dwordx4 v[12:15], v[0:1], off
	global_load_dwordx4 v[8:11], v[0:1], off offset:1024
	global_load_dwordx4 v[4:7], v[0:1], off offset:2048
	s_nop 0
	global_load_dwordx4 v[0:3], v[0:1], off offset:3072
	s_nop 0
	global_load_dwordx4 v[40:43], v[66:67], off
	global_load_dwordx4 v[36:39], v[66:67], off offset:1024
	global_load_dwordx4 v[28:31], v[66:67], off offset:2048
	global_load_dwordx4 v[20:23], v[66:67], off offset:3072
	s_waitcnt vmcnt(8)
	v_pk_mul_f32 v[96:97], v[82:83], v[82:83]
	v_pk_mul_f32 v[98:99], v[80:81], v[80:81]
	v_mul_f32_e32 v79, v92, v92
	v_pk_mov_b32 v[100:101], v[98:99], v[96:97] op_sel:[1,0]
	v_mov_b32_e32 v99, v97
	v_pk_add_f32 v[96:97], v[100:101], v[98:99]
	v_pk_mul_f32 v[98:99], v[86:87], v[86:87]
	v_pk_mul_f32 v[100:101], v[84:85], v[84:85]
	v_pk_add_f32 v[96:97], v[96:97], v[96:97] op_sel:[0,1] op_sel_hi:[1,0]
	v_pk_mov_b32 v[102:103], v[100:101], v[98:99] op_sel:[1,0]
	v_mov_b32_e32 v101, v99
	v_pk_add_f32 v[98:99], v[102:103], v[100:101]
	v_mul_f32_e32 v100, v93, v93
	v_pk_add_f32 v[98:99], v[98:99], v[98:99] op_sel:[0,1] op_sel_hi:[1,0]
	v_mov_b32_e32 v97, v79
	v_mov_b32_e32 v99, v100
	v_pk_add_f32 v[96:97], v[96:97], v[98:99]
	v_mul_f32_e32 v98, v89, v89
	v_mul_f32_e32 v101, v94, v94
	v_pk_fma_f32 v[98:99], v[88:89], v[88:89], v[98:99] op_sel_hi:[1,1,0]
	v_mul_f32_e32 v100, v91, v91
	v_mul_f32_e32 v102, v95, v95
	v_mov_b32_e32 v99, v101
	v_pk_fma_f32 v[100:101], v[90:91], v[90:91], v[100:101] op_sel_hi:[1,1,0]
	v_lshl_add_u64 v[70:71], v[70:71], 0, s[4:5]
	v_mov_b32_e32 v101, v102
	v_pk_add_f32 v[98:99], v[98:99], v[100:101]
	s_nop 0
	v_pk_add_f32 v[96:97], v[96:97], v[98:99]
	s_nop 0
	v_add_f32_e32 v79, v96, v97
	s_waitcnt lgkmcnt(0)
	s_nop 1
	v_add_f32_dpp v79, v79, v79 quad_perm:[1,0,3,2] row_mask:0xf bank_mask:0xf
	s_waitcnt lgkmcnt(0)
	s_nop 1
	v_add_f32_dpp v79, v79, v79 quad_perm:[2,3,0,1] row_mask:0xf bank_mask:0xf
	s_waitcnt lgkmcnt(0)
	s_nop 1
	v_add_f32_dpp v79, v79, v79 row_half_mirror row_mask:0xf bank_mask:0xf
	s_waitcnt lgkmcnt(0)
	s_nop 1
	v_add_f32_dpp v79, v79, v79 row_mirror row_mask:0xf bank_mask:0xf
	v_mov_b32_e32 v96, v79
	s_waitcnt lgkmcnt(0)
	s_nop 1
	v_permlane16_swap_b32_e32 v96, v79
	v_add_f32_e32 v79, v79, v96
	v_mov_b32_e32 v96, v79
	s_waitcnt lgkmcnt(0)
	s_nop 1
	v_permlane32_swap_b32_e32 v96, v79
	v_add_f32_e32 v79, v79, v96
	v_fmamk_f32 v79, v79, 0x3a800000, v78
	v_cmp_gt_f32_e32 vcc, s1, v79
	v_mul_f32_e32 v96, 0x4b800000, v79
	s_nop 0
	v_cndmask_b32_e32 v79, v79, v96, vcc
	v_rsq_f32_e32 v79, v79
	s_nop 0
	v_mul_f32_e32 v96, 0x45800000, v79
	v_cndmask_b32_e32 v79, v79, v96, vcc
	v_mul_f32_e32 v80, v80, v79
	v_mul_f32_e32 v81, v81, v79
	s_waitcnt vmcnt(3)
	v_mul_f32_e32 v80, v40, v80
	v_mul_f32_e32 v81, v41, v81
	v_cvt_pk_bf16_f32 v80, v80, v81
	v_mul_f32_e32 v81, v82, v79
	v_mul_f32_e32 v81, v42, v81
	v_mul_f32_e32 v82, v83, v79
	v_mul_f32_e32 v82, v43, v82
	v_cvt_pk_bf16_f32 v81, v81, v82
	global_store_dwordx2 v[68:69], v[80:81], off
	v_mul_f32_e32 v80, v84, v79
	v_mul_f32_e32 v81, v85, v79
	s_waitcnt vmcnt(3)
	v_mul_f32_e32 v80, v36, v80
	v_mul_f32_e32 v81, v37, v81
	v_cvt_pk_bf16_f32 v80, v80, v81
	v_mul_f32_e32 v81, v86, v79
	v_mul_f32_e32 v81, v38, v81
	v_mul_f32_e32 v82, v87, v79
	v_mul_f32_e32 v82, v39, v82
	v_cvt_pk_bf16_f32 v81, v81, v82
	global_store_dwordx2 v[68:69], v[80:81], off offset:512
	v_mul_f32_e32 v80, v88, v79
	v_mul_f32_e32 v81, v89, v79
	s_waitcnt vmcnt(3)
	v_mul_f32_e32 v80, v28, v80
	v_mul_f32_e32 v81, v29, v81
	v_cvt_pk_bf16_f32 v80, v80, v81
	v_mul_f32_e32 v81, v90, v79
	v_mul_f32_e32 v81, v30, v81
	v_mul_f32_e32 v82, v91, v79
	v_mul_f32_e32 v82, v31, v82
	v_cvt_pk_bf16_f32 v81, v81, v82
	global_store_dwordx2 v[68:69], v[80:81], off offset:1024
	v_mul_f32_e32 v80, v92, v79
	v_mul_f32_e32 v81, v93, v79
	s_waitcnt vmcnt(3)
	v_mul_f32_e32 v80, v20, v80
	v_mul_f32_e32 v81, v21, v81
	v_cvt_pk_bf16_f32 v80, v80, v81
	v_mul_f32_e32 v81, v94, v79
	v_mul_f32_e32 v81, v22, v81
	v_mul_f32_e32 v79, v95, v79
	v_mul_f32_e32 v79, v23, v79
	v_cvt_pk_bf16_f32 v81, v81, v79
	global_store_dwordx2 v[68:69], v[80:81], off offset:1536
	v_pk_mul_f32 v[80:81], v[62:63], v[62:63]
	v_pk_mul_f32 v[82:83], v[60:61], v[60:61]
	v_mul_f32_e32 v79, v48, v48
	v_pk_mov_b32 v[84:85], v[82:83], v[80:81] op_sel:[1,0]
	v_mov_b32_e32 v83, v81
	v_pk_add_f32 v[80:81], v[84:85], v[82:83]
	v_pk_mul_f32 v[82:83], v[58:59], v[58:59]
	v_pk_mul_f32 v[84:85], v[56:57], v[56:57]
	v_pk_add_f32 v[80:81], v[80:81], v[80:81] op_sel:[0,1] op_sel_hi:[1,0]
	v_pk_mov_b32 v[86:87], v[84:85], v[82:83] op_sel:[1,0]
	v_mov_b32_e32 v85, v83
	v_pk_add_f32 v[82:83], v[86:87], v[84:85]
	v_mul_f32_e32 v84, v49, v49
	v_pk_add_f32 v[82:83], v[82:83], v[82:83] op_sel:[0,1] op_sel_hi:[1,0]
	v_mov_b32_e32 v81, v79
	v_mov_b32_e32 v83, v84
	v_pk_add_f32 v[80:81], v[80:81], v[82:83]
	v_mul_f32_e32 v82, v53, v53
	v_mul_f32_e32 v85, v50, v50
	v_pk_fma_f32 v[82:83], v[52:53], v[52:53], v[82:83] op_sel_hi:[1,1,0]
	v_mul_f32_e32 v84, v55, v55
	v_mul_f32_e32 v86, v51, v51
	v_mov_b32_e32 v83, v85
	v_pk_fma_f32 v[84:85], v[54:55], v[54:55], v[84:85] op_sel_hi:[1,1,0]
	s_nop 0
	v_mov_b32_e32 v85, v86
	v_pk_add_f32 v[82:83], v[82:83], v[84:85]
	s_nop 0
	v_pk_add_f32 v[80:81], v[80:81], v[82:83]
	s_nop 0
	v_add_f32_e32 v79, v80, v81
	s_waitcnt lgkmcnt(0)
	s_nop 1
	v_add_f32_dpp v79, v79, v79 quad_perm:[1,0,3,2] row_mask:0xf bank_mask:0xf
	s_waitcnt lgkmcnt(0)
	s_nop 1
	v_add_f32_dpp v79, v79, v79 quad_perm:[2,3,0,1] row_mask:0xf bank_mask:0xf
	s_waitcnt lgkmcnt(0)
	s_nop 1
	v_add_f32_dpp v79, v79, v79 row_half_mirror row_mask:0xf bank_mask:0xf
	s_waitcnt lgkmcnt(0)
	s_nop 1
	v_add_f32_dpp v79, v79, v79 row_mirror row_mask:0xf bank_mask:0xf
	v_mov_b32_e32 v80, v79
	s_waitcnt lgkmcnt(0)
	s_nop 1
	v_permlane16_swap_b32_e32 v80, v79
	v_add_f32_e32 v79, v79, v80
	v_mov_b32_e32 v80, v79
	s_waitcnt lgkmcnt(0)
	s_nop 1
	v_permlane32_swap_b32_e32 v80, v79
	v_add_f32_e32 v79, v79, v80
	v_fmamk_f32 v79, v79, 0x3a800000, v78
	v_cmp_gt_f32_e32 vcc, s1, v79
	v_mul_f32_e32 v80, 0x4b800000, v79
	s_nop 0
	v_cndmask_b32_e32 v79, v79, v80, vcc
	v_rsq_f32_e32 v79, v79
	s_nop 0
	v_mul_f32_e32 v80, 0x45800000, v79
	v_cndmask_b32_e32 v79, v79, v80, vcc
	v_mul_f32_e32 v48, v48, v79
	v_mul_f32_e32 v49, v49, v79
	v_mul_f32_e32 v52, v52, v79
	v_mul_f32_e32 v53, v53, v79
	v_mul_f32_e32 v48, v20, v48
	v_mul_f32_e32 v49, v21, v49
	v_mul_f32_e32 v52, v28, v52
	v_mul_f32_e32 v53, v29, v53
	v_cvt_pk_bf16_f32 v48, v48, v49
	v_mul_f32_e32 v49, v50, v79
	v_cvt_pk_bf16_f32 v52, v52, v53
	v_mul_f32_e32 v53, v54, v79
	v_mul_f32_e32 v49, v22, v49
	v_mul_f32_e32 v50, v51, v79
	v_mul_f32_e32 v53, v30, v53
	v_mul_f32_e32 v54, v55, v79
	v_mul_f32_e32 v50, v23, v50
	v_cvt_pk_bf16_f32 v49, v49, v50
	v_mul_f32_e32 v54, v31, v54
	v_cvt_pk_bf16_f32 v53, v53, v54
	global_store_dwordx2 v[68:69], v[48:49], off offset:3584
	v_pk_mul_f32 v[48:49], v[46:47], v[46:47]
	v_pk_mul_f32 v[50:51], v[44:45], v[44:45]
	global_store_dwordx2 v[68:69], v[52:53], off offset:3072
	v_pk_mov_b32 v[52:53], v[50:51], v[48:49] op_sel:[1,0]
	v_mov_b32_e32 v51, v49
	v_pk_add_f32 v[48:49], v[52:53], v[50:51]
	v_pk_mul_f32 v[50:51], v[34:35], v[34:35]
	v_pk_mul_f32 v[52:53], v[32:33], v[32:33]
	v_pk_add_f32 v[48:49], v[48:49], v[48:49] op_sel:[0,1] op_sel_hi:[1,0]
	v_pk_mov_b32 v[54:55], v[52:53], v[50:51] op_sel:[1,0]
	v_mov_b32_e32 v53, v51
	v_pk_add_f32 v[50:51], v[54:55], v[52:53]
	v_mul_f32_e32 v52, v16, v16
	v_mul_f32_e32 v53, v17, v17
	v_pk_add_f32 v[50:51], v[50:51], v[50:51] op_sel:[0,1] op_sel_hi:[1,0]
	v_mov_b32_e32 v49, v52
	v_mov_b32_e32 v51, v53
	v_pk_add_f32 v[48:49], v[48:49], v[50:51]
	v_mul_f32_e32 v50, v25, v25
	v_mul_f32_e32 v52, v27, v27
	v_mul_f32_e32 v54, v18, v18
	v_mul_f32_e32 v55, v19, v19
	v_pk_fma_f32 v[50:51], v[24:25], v[24:25], v[50:51] op_sel_hi:[1,1,0]
	v_pk_fma_f32 v[52:53], v[26:27], v[26:27], v[52:53] op_sel_hi:[1,1,0]
	v_mov_b32_e32 v51, v54
	v_mov_b32_e32 v53, v55
	v_pk_add_f32 v[50:51], v[50:51], v[52:53]
	v_mul_f32_e32 v60, v60, v79
	v_pk_add_f32 v[48:49], v[48:49], v[50:51]
	v_mul_f32_e32 v61, v61, v79
	v_add_f32_e32 v48, v48, v49
	v_mul_f32_e32 v56, v56, v79
	v_mul_f32_e32 v57, v57, v79
	v_mul_f32_e32 v60, v40, v60
	v_mul_f32_e32 v61, v41, v61
	s_waitcnt lgkmcnt(0)
	s_nop 1
	v_add_f32_dpp v48, v48, v48 quad_perm:[1,0,3,2] row_mask:0xf bank_mask:0xf
	v_mul_f32_e32 v56, v36, v56
	v_mul_f32_e32 v57, v37, v57
	v_cvt_pk_bf16_f32 v60, v60, v61
	v_mul_f32_e32 v61, v62, v79
	s_waitcnt lgkmcnt(0)
	s_nop 1
	v_add_f32_dpp v48, v48, v48 quad_perm:[2,3,0,1] row_mask:0xf bank_mask:0xf
	v_cvt_pk_bf16_f32 v56, v56, v57
	v_mul_f32_e32 v57, v58, v79
	v_mul_f32_e32 v61, v42, v61
	v_mul_f32_e32 v62, v63, v79
	s_waitcnt lgkmcnt(0)
	s_nop 1
	v_add_f32_dpp v48, v48, v48 row_half_mirror row_mask:0xf bank_mask:0xf
	v_mul_f32_e32 v57, v38, v57
	v_mul_f32_e32 v58, v59, v79
	v_mul_f32_e32 v62, v43, v62
	v_cvt_pk_bf16_f32 v61, v61, v62
	s_waitcnt lgkmcnt(0)
	s_nop 1
	v_add_f32_dpp v48, v48, v48 row_mirror row_mask:0xf bank_mask:0xf
	v_mov_b32_e32 v49, v48
	global_store_dwordx2 v[68:69], v[60:61], off offset:2048
	v_mul_f32_e32 v58, v39, v58
	v_cvt_pk_bf16_f32 v57, v57, v58
	global_store_dwordx2 v[68:69], v[56:57], off offset:2560
	s_waitcnt lgkmcnt(0)
	s_nop 1
	v_permlane16_swap_b32_e32 v49, v48
	v_add_f32_e32 v48, v48, v49
	v_mov_b32_e32 v49, v48
	s_waitcnt lgkmcnt(0)
	s_nop 1
	v_permlane32_swap_b32_e32 v49, v48
	v_add_f32_e32 v48, v48, v49
	v_fmamk_f32 v48, v48, 0x3a800000, v78
	v_cmp_gt_f32_e32 vcc, s1, v48
	v_mul_f32_e32 v49, 0x4b800000, v48
	s_nop 0
	v_cndmask_b32_e32 v48, v48, v49, vcc
	v_rsq_f32_e32 v48, v48
	s_nop 0
	v_mul_f32_e32 v49, 0x45800000, v48
	v_cndmask_b32_e32 v48, v48, v49, vcc
	v_mul_f32_e32 v44, v44, v48
	v_mul_f32_e32 v45, v45, v48
	v_mul_f32_e32 v44, v40, v44
	v_mul_f32_e32 v45, v41, v45
	v_mul_f32_e32 v16, v16, v48
	v_mul_f32_e32 v17, v17, v48
	v_cvt_pk_bf16_f32 v44, v44, v45
	v_mul_f32_e32 v45, v46, v48
	v_mul_f32_e32 v46, v47, v48
	v_mul_f32_e32 v24, v24, v48
	v_mul_f32_e32 v25, v25, v48
	v_mul_f32_e32 v16, v20, v16
	v_mul_f32_e32 v17, v21, v17
	v_mul_f32_e32 v45, v42, v45
	v_mul_f32_e32 v46, v43, v46
	v_mul_f32_e32 v24, v28, v24
	v_mul_f32_e32 v25, v29, v25
	v_cvt_pk_bf16_f32 v16, v16, v17
	v_mul_f32_e32 v17, v18, v48
	v_cvt_pk_bf16_f32 v45, v45, v46
	v_add_co_u32_e32 v46, vcc, s7, v68
	v_cvt_pk_bf16_f32 v24, v24, v25
	v_mul_f32_e32 v25, v26, v48
	v_mul_f32_e32 v17, v22, v17
	v_mul_f32_e32 v18, v19, v48
	v_addc_co_u32_e32 v47, vcc, 0, v69, vcc
	v_mul_f32_e32 v25, v30, v25
	v_mul_f32_e32 v26, v27, v48
	v_mul_f32_e32 v18, v23, v18
	v_cvt_pk_bf16_f32 v17, v17, v18
	v_mul_f32_e32 v26, v31, v26
	v_cvt_pk_bf16_f32 v25, v25, v26
	global_store_dwordx2 v[46:47], v[16:17], off offset:1536
	v_pk_mul_f32 v[16:17], v[14:15], v[14:15]
	v_pk_mul_f32 v[18:19], v[12:13], v[12:13]
	global_store_dwordx2 v[46:47], v[24:25], off offset:1024
	v_pk_mov_b32 v[24:25], v[18:19], v[16:17] op_sel:[1,0]
	v_mov_b32_e32 v19, v17
	v_pk_add_f32 v[16:17], v[24:25], v[18:19]
	v_pk_mul_f32 v[18:19], v[10:11], v[10:11]
	v_pk_mul_f32 v[24:25], v[8:9], v[8:9]
	v_pk_add_f32 v[16:17], v[16:17], v[16:17] op_sel:[0,1] op_sel_hi:[1,0]
	v_pk_mov_b32 v[26:27], v[24:25], v[18:19] op_sel:[1,0]
	v_mov_b32_e32 v25, v19
	v_pk_add_f32 v[18:19], v[26:27], v[24:25]
	v_mul_f32_e32 v24, v0, v0
	v_mul_f32_e32 v25, v1, v1
	v_pk_add_f32 v[18:19], v[18:19], v[18:19] op_sel:[0,1] op_sel_hi:[1,0]
	v_mov_b32_e32 v17, v24
	v_mov_b32_e32 v19, v25
	v_pk_add_f32 v[16:17], v[16:17], v[18:19]
	v_mul_f32_e32 v18, v5, v5
	v_mul_f32_e32 v24, v7, v7
	v_mul_f32_e32 v26, v2, v2
	v_mul_f32_e32 v27, v3, v3
	v_pk_fma_f32 v[18:19], v[4:5], v[4:5], v[18:19] op_sel_hi:[1,1,0]
	v_pk_fma_f32 v[24:25], v[6:7], v[6:7], v[24:25] op_sel_hi:[1,1,0]
	v_mov_b32_e32 v19, v26
	v_mov_b32_e32 v25, v27
	v_pk_add_f32 v[18:19], v[18:19], v[24:25]
	v_mul_f32_e32 v32, v32, v48
	v_pk_add_f32 v[16:17], v[16:17], v[18:19]
	v_mul_f32_e32 v33, v33, v48
	v_add_f32_e32 v16, v16, v17
	v_mul_f32_e32 v32, v36, v32
	v_mul_f32_e32 v33, v37, v33
	v_cvt_pk_bf16_f32 v32, v32, v33
	v_mul_f32_e32 v33, v34, v48
	s_waitcnt lgkmcnt(0)
	s_nop 1
	v_add_f32_dpp v16, v16, v16 quad_perm:[1,0,3,2] row_mask:0xf bank_mask:0xf
	v_mul_f32_e32 v33, v38, v33
	v_mul_f32_e32 v34, v35, v48
	v_lshl_add_u64 v[68:69], v[68:69], 0, s[2:3]
	global_store_dwordx2 v[46:47], v[44:45], off
	s_waitcnt lgkmcnt(0)
	s_nop 1
	v_add_f32_dpp v16, v16, v16 quad_perm:[2,3,0,1] row_mask:0xf bank_mask:0xf
	v_mul_f32_e32 v34, v39, v34
	v_cvt_pk_bf16_f32 v33, v33, v34
	global_store_dwordx2 v[46:47], v[32:33], off offset:512
	s_waitcnt lgkmcnt(0)
	s_nop 1
	v_add_f32_dpp v16, v16, v16 row_half_mirror row_mask:0xf bank_mask:0xf
	s_waitcnt lgkmcnt(0)
	s_nop 1
	v_add_f32_dpp v16, v16, v16 row_mirror row_mask:0xf bank_mask:0xf
	v_mov_b32_e32 v17, v16
	s_waitcnt lgkmcnt(0)
	s_nop 1
	v_permlane16_swap_b32_e32 v17, v16
	v_add_f32_e32 v16, v16, v17
	v_mov_b32_e32 v17, v16
	s_waitcnt lgkmcnt(0)
	s_nop 1
	v_permlane32_swap_b32_e32 v17, v16
	v_add_f32_e32 v16, v16, v17
	v_fmamk_f32 v16, v16, 0x3a800000, v78
	v_cmp_gt_f32_e32 vcc, s1, v16
	v_mul_f32_e32 v17, 0x4b800000, v16
	s_nop 0
	v_cndmask_b32_e32 v16, v16, v17, vcc
	v_rsq_f32_e32 v16, v16
	s_nop 0
	v_mul_f32_e32 v17, 0x45800000, v16
	v_cndmask_b32_e32 v16, v16, v17, vcc
	v_mul_f32_e32 v12, v12, v16
	v_mul_f32_e32 v13, v13, v16
	v_mul_f32_e32 v8, v8, v16
	v_mul_f32_e32 v9, v9, v16
	v_mul_f32_e32 v4, v4, v16
	v_mul_f32_e32 v5, v5, v16
	v_mul_f32_e32 v0, v0, v16
	v_mul_f32_e32 v1, v1, v16
	v_mul_f32_e32 v12, v40, v12
	v_mul_f32_e32 v13, v41, v13
	v_mul_f32_e32 v8, v36, v8
	v_mul_f32_e32 v9, v37, v9
	v_mul_f32_e32 v4, v28, v4
	v_mul_f32_e32 v5, v29, v5
	v_mul_f32_e32 v0, v20, v0
	v_mul_f32_e32 v1, v21, v1
	v_cvt_pk_bf16_f32 v12, v12, v13
	v_mul_f32_e32 v13, v14, v16
	v_cvt_pk_bf16_f32 v8, v8, v9
	v_mul_f32_e32 v9, v10, v16
	v_cvt_pk_bf16_f32 v4, v4, v5
	v_mul_f32_e32 v5, v6, v16
	v_cvt_pk_bf16_f32 v0, v0, v1
	v_mul_f32_e32 v1, v2, v16
	v_mul_f32_e32 v13, v42, v13
	v_mul_f32_e32 v14, v15, v16
	v_mul_f32_e32 v9, v38, v9
	v_mul_f32_e32 v10, v11, v16
	v_mul_f32_e32 v5, v30, v5
	v_mul_f32_e32 v6, v7, v16
	v_mul_f32_e32 v1, v22, v1
	v_mul_f32_e32 v2, v3, v16
	v_mul_f32_e32 v14, v43, v14
	v_cvt_pk_bf16_f32 v13, v13, v14
	global_store_dwordx2 v[46:47], v[12:13], off offset:2048
	v_mul_f32_e32 v10, v39, v10
	v_cvt_pk_bf16_f32 v9, v9, v10
	global_store_dwordx2 v[46:47], v[8:9], off offset:2560
	v_mul_f32_e32 v6, v31, v6
	v_cvt_pk_bf16_f32 v5, v5, v6
	global_store_dwordx2 v[46:47], v[4:5], off offset:3072
	v_mul_f32_e32 v2, v23, v2
	v_cvt_pk_bf16_f32 v1, v1, v2
	global_store_dwordx2 v[46:47], v[0:1], off offset:3584
	s_cbranch_scc0 .LBB0_561

.LBB0_564:
	global_load_dwordx4 v[100:103], v[20:21], off
	global_load_dwordx4 v[104:107], v[20:21], off offset:1024
	global_load_dwordx4 v[108:111], v[20:21], off offset:2048
	global_load_dwordx4 v[112:115], v[20:21], off offset:3072
	v_lshl_add_u64 v[0:1], s[0:1], 0, v[18:19]
	v_add_co_u32_e32 v22, vcc, 0x4000000, v0
	s_mov_b32 s6, 0x14914000
	s_nop 0
	v_addc_co_u32_e32 v23, vcc, 0, v1, vcc
	v_lshl_add_u64 v[0:1], s[4:5], 0, v[18:19]
	v_add_co_u32_e32 v14, vcc, 0x14114000, v0
	global_load_dwordx4 v[2:5], v[22:23], off
	global_load_dwordx4 v[6:9], v[22:23], off offset:1024
	global_load_dwordx4 v[10:13], v[22:23], off offset:2048
	global_load_dwordx4 v[32:35], v[22:23], off offset:3072
	v_addc_co_u32_e32 v15, vcc, 0, v1, vcc
	global_load_dwordx4 v[36:39], v[14:15], off
	global_load_dwordx4 v[40:43], v[14:15], off offset:1024
	global_load_dwordx4 v[44:47], v[14:15], off offset:2048
	global_load_dwordx4 v[48:51], v[14:15], off offset:3072
	v_add_co_u32_e32 v14, vcc, 0x14314000, v0
	s_waitcnt vmcnt(0)
	v_pk_add_f32 v[4:5], v[4:5], v[38:39]
	v_addc_co_u32_e32 v15, vcc, 0, v1, vcc
	global_load_dwordx4 v[52:55], v[14:15], off
	global_load_dwordx4 v[56:59], v[14:15], off offset:1024
	global_load_dwordx4 v[60:63], v[14:15], off offset:2048
	global_load_dwordx4 v[64:67], v[14:15], off offset:3072
	v_add_co_u32_e32 v14, vcc, 0x14514000, v0
	v_pk_add_f32 v[32:33], v[32:33], v[48:49]
	s_nop 0
	v_addc_co_u32_e32 v15, vcc, 0, v1, vcc
	global_load_dwordx4 v[68:71], v[14:15], off
	global_load_dwordx4 v[72:75], v[14:15], off offset:1024
	global_load_dwordx4 v[76:79], v[14:15], off offset:2048
	global_load_dwordx4 v[80:83], v[14:15], off offset:3072
	v_add_co_u32_e32 v14, vcc, 0x14714000, v0
	v_pk_add_f32 v[2:3], v[2:3], v[36:37]
	s_nop 0
	v_addc_co_u32_e32 v15, vcc, 0, v1, vcc
	global_load_dwordx4 v[84:87], v[14:15], off
	global_load_dwordx4 v[88:91], v[14:15], off offset:1024
	global_load_dwordx4 v[92:95], v[14:15], off offset:2048
	global_load_dwordx4 v[96:99], v[14:15], off offset:3072
	v_pk_add_f32 v[8:9], v[8:9], v[42:43]
	v_pk_add_f32 v[6:7], v[6:7], v[40:41]
	v_pk_add_f32 v[12:13], v[12:13], v[46:47]
	v_pk_add_f32 v[10:11], v[10:11], v[44:45]
	v_pk_add_f32 v[14:15], v[34:35], v[50:51]
	s_waitcnt vmcnt(11)
	v_pk_add_f32 v[4:5], v[4:5], v[54:55]
	v_pk_add_f32 v[2:3], v[2:3], v[52:53]
	s_waitcnt vmcnt(10)
	v_pk_add_f32 v[8:9], v[8:9], v[58:59]
	s_waitcnt vmcnt(8)
	v_pk_add_f32 v[32:33], v[32:33], v[64:65]
	v_pk_add_f32 v[6:7], v[6:7], v[56:57]
	v_pk_add_f32 v[12:13], v[12:13], v[62:63]
	v_pk_add_f32 v[10:11], v[10:11], v[60:61]
	s_waitcnt vmcnt(7)
	v_pk_add_f32 v[4:5], v[4:5], v[70:71]
	v_pk_add_f32 v[2:3], v[2:3], v[68:69]
	s_waitcnt vmcnt(4)
	v_pk_add_f32 v[32:33], v[32:33], v[80:81]
	v_pk_add_f32 v[8:9], v[8:9], v[74:75]
	v_pk_add_f32 v[6:7], v[6:7], v[72:73]
	v_pk_add_f32 v[12:13], v[12:13], v[78:79]
	v_pk_add_f32 v[10:11], v[10:11], v[76:77]
	s_waitcnt vmcnt(3)
	v_pk_add_f32 v[86:87], v[4:5], v[86:87]
	s_waitcnt vmcnt(0)
	v_pk_add_f32 v[96:97], v[32:33], v[96:97]
	v_add_co_u32_e32 v32, vcc, s6, v0
	s_mov_b32 s6, 0x14b14000
	s_nop 0
	v_addc_co_u32_e32 v33, vcc, 0, v1, vcc
	v_add_co_u32_e32 v48, vcc, s6, v0
	s_mov_b32 s6, 0x14d14000
	s_nop 0
	v_addc_co_u32_e32 v49, vcc, 0, v1, vcc
	v_add_co_u32_e32 v64, vcc, s6, v0
	v_pk_add_f32 v[84:85], v[2:3], v[84:85]
	v_pk_add_f32 v[90:91], v[8:9], v[90:91]
	v_pk_add_f32 v[88:89], v[6:7], v[88:89]
	v_pk_add_f32 v[94:95], v[12:13], v[94:95]
	v_pk_add_f32 v[92:93], v[10:11], v[92:93]
	global_load_dwordx4 v[2:5], v[32:33], off
	global_load_dwordx4 v[6:9], v[32:33], off offset:1024
	global_load_dwordx4 v[10:13], v[32:33], off offset:2048
	s_nop 0
	global_load_dwordx4 v[32:35], v[32:33], off offset:3072
	v_addc_co_u32_e32 v65, vcc, 0, v1, vcc
	s_mov_b32 s6, 0x14f14000
	global_load_dwordx4 v[36:39], v[48:49], off
	global_load_dwordx4 v[40:43], v[48:49], off offset:1024
	global_load_dwordx4 v[44:47], v[48:49], off offset:2048
	s_nop 0
	global_load_dwordx4 v[48:51], v[48:49], off offset:3072
	v_add_co_u32_e32 v80, vcc, s6, v0
	v_pk_add_f32 v[14:15], v[14:15], v[66:67]
	global_load_dwordx4 v[52:55], v[64:65], off
	global_load_dwordx4 v[56:59], v[64:65], off offset:1024
	global_load_dwordx4 v[60:63], v[64:65], off offset:2048
	s_nop 0
	global_load_dwordx4 v[64:67], v[64:65], off offset:3072
	v_addc_co_u32_e32 v81, vcc, 0, v1, vcc
	v_pk_add_f32 v[14:15], v[14:15], v[82:83]
	global_load_dwordx4 v[68:71], v[80:81], off
	global_load_dwordx4 v[72:75], v[80:81], off offset:1024
	global_load_dwordx4 v[76:79], v[80:81], off offset:2048
	s_nop 0
	global_load_dwordx4 v[80:83], v[80:81], off offset:3072
	s_mov_b32 s6, 0x15114000
	v_pk_add_f32 v[14:15], v[14:15], v[98:99]
	s_waitcnt vmcnt(15)
	v_pk_add_f32 v[4:5], v[86:87], v[4:5]
	v_pk_add_f32 v[2:3], v[84:85], v[2:3]
	s_waitcnt vmcnt(14)
	v_pk_add_f32 v[8:9], v[90:91], v[8:9]
	s_waitcnt vmcnt(12)
	v_pk_add_f32 v[32:33], v[96:97], v[32:33]
	v_pk_add_f32 v[6:7], v[88:89], v[6:7]
	v_pk_add_f32 v[12:13], v[94:95], v[12:13]
	v_pk_add_f32 v[10:11], v[92:93], v[10:11]
	s_waitcnt vmcnt(8)
	v_pk_add_f32 v[32:33], v[32:33], v[48:49]
	v_pk_add_f32 v[4:5], v[4:5], v[38:39]
	v_pk_add_f32 v[2:3], v[2:3], v[36:37]
	v_pk_add_f32 v[8:9], v[8:9], v[42:43]
	s_waitcnt vmcnt(4)
	v_pk_add_f32 v[32:33], v[32:33], v[64:65]
	v_pk_add_f32 v[6:7], v[6:7], v[40:41]
	v_pk_add_f32 v[12:13], v[12:13], v[46:47]
	v_pk_add_f32 v[10:11], v[10:11], v[44:45]
	s_waitcnt vmcnt(0)
	v_pk_add_f32 v[80:81], v[32:33], v[80:81]
	v_add_co_u32_e32 v32, vcc, s6, v0
	s_mov_b32 s6, 0x15314000
	s_nop 0
	v_addc_co_u32_e32 v33, vcc, 0, v1, vcc
	v_add_co_u32_e32 v48, vcc, s6, v0
	v_pk_add_f32 v[4:5], v[4:5], v[54:55]
	v_pk_add_f32 v[2:3], v[2:3], v[52:53]
	v_pk_add_f32 v[8:9], v[8:9], v[58:59]
	v_pk_add_f32 v[6:7], v[6:7], v[56:57]
	v_pk_add_f32 v[12:13], v[12:13], v[62:63]
	v_pk_add_f32 v[10:11], v[10:11], v[60:61]
	v_addc_co_u32_e32 v49, vcc, 0, v1, vcc
	s_mov_b32 s6, 0x15514000
	v_pk_add_f32 v[14:15], v[14:15], v[34:35]
	v_pk_add_f32 v[70:71], v[4:5], v[70:71]
	v_pk_add_f32 v[68:69], v[2:3], v[68:69]
	v_pk_add_f32 v[74:75], v[8:9], v[74:75]
	v_pk_add_f32 v[72:73], v[6:7], v[72:73]
	v_pk_add_f32 v[78:79], v[12:13], v[78:79]
	v_pk_add_f32 v[76:77], v[10:11], v[76:77]
	global_load_dwordx4 v[2:5], v[32:33], off
	global_load_dwordx4 v[6:9], v[32:33], off offset:1024
	global_load_dwordx4 v[10:13], v[32:33], off offset:2048
	s_nop 0
	global_load_dwordx4 v[32:35], v[32:33], off offset:3072
	v_add_co_u32_e32 v0, vcc, s6, v0
	v_pk_add_f32 v[14:15], v[14:15], v[50:51]
	global_load_dwordx4 v[36:39], v[48:49], off
	global_load_dwordx4 v[40:43], v[48:49], off offset:1024
	global_load_dwordx4 v[44:47], v[48:49], off offset:2048
	s_nop 0
	global_load_dwordx4 v[48:51], v[48:49], off offset:3072
	v_addc_co_u32_e32 v1, vcc, 0, v1, vcc
	v_pk_add_f32 v[14:15], v[14:15], v[66:67]
	global_load_dwordx4 v[52:55], v[0:1], off
	global_load_dwordx4 v[56:59], v[0:1], off offset:1024
	global_load_dwordx4 v[60:63], v[0:1], off offset:2048
	global_load_dwordx4 v[64:67], v[0:1], off offset:3072
	v_pk_add_f32 v[14:15], v[14:15], v[82:83]
	s_mov_b32 s6, 0x800000
	s_waitcnt vmcnt(11)
	v_pk_add_f32 v[0:1], v[70:71], v[4:5]
	v_pk_add_f32 v[2:3], v[68:69], v[2:3]
	s_waitcnt vmcnt(10)
	v_pk_add_f32 v[4:5], v[74:75], v[8:9]
	v_pk_add_f32 v[6:7], v[72:73], v[6:7]
	s_waitcnt vmcnt(9)
	v_pk_add_f32 v[8:9], v[78:79], v[12:13]
	v_pk_add_f32 v[10:11], v[76:77], v[10:11]
	s_waitcnt vmcnt(8)
	v_pk_add_f32 v[12:13], v[14:15], v[34:35]
	v_pk_add_f32 v[14:15], v[80:81], v[32:33]
	s_waitcnt vmcnt(7)
	v_pk_add_f32 v[0:1], v[0:1], v[38:39]
	v_pk_add_f32 v[2:3], v[2:3], v[36:37]
	s_waitcnt vmcnt(6)
	v_pk_add_f32 v[4:5], v[4:5], v[42:43]
	v_pk_add_f32 v[6:7], v[6:7], v[40:41]
	s_waitcnt vmcnt(5)
	v_pk_add_f32 v[8:9], v[8:9], v[46:47]
	v_pk_add_f32 v[10:11], v[10:11], v[44:45]
	s_waitcnt vmcnt(4)
	v_pk_add_f32 v[12:13], v[12:13], v[50:51]
	v_pk_add_f32 v[14:15], v[14:15], v[48:49]
	s_waitcnt vmcnt(3)
	v_pk_add_f32 v[0:1], v[0:1], v[54:55]
	v_pk_add_f32 v[2:3], v[2:3], v[52:53]
	s_waitcnt vmcnt(2)
	v_pk_add_f32 v[4:5], v[4:5], v[58:59]
	v_pk_add_f32 v[6:7], v[6:7], v[56:57]
	s_waitcnt vmcnt(1)
	v_pk_add_f32 v[32:33], v[8:9], v[62:63]
	v_pk_add_f32 v[34:35], v[10:11], v[60:61]
	s_waitcnt vmcnt(0)
	v_pk_add_f32 v[36:37], v[12:13], v[66:67]
	v_pk_add_f32 v[38:39], v[14:15], v[64:65]
	v_pk_fma_f32 v[14:15], v[54:55], 0, v[0:1] op_sel_hi:[1,0,1]
	v_pk_fma_f32 v[12:13], v[52:53], 0, v[2:3] op_sel_hi:[1,0,1]
	v_pk_fma_f32 v[10:11], v[58:59], 0, v[4:5] op_sel_hi:[1,0,1]
	v_pk_fma_f32 v[8:9], v[56:57], 0, v[6:7] op_sel_hi:[1,0,1]
	v_pk_fma_f32 v[6:7], v[62:63], 0, v[32:33] op_sel_hi:[1,0,1]
	v_pk_fma_f32 v[4:5], v[60:61], 0, v[34:35] op_sel_hi:[1,0,1]
	v_pk_mul_f32 v[32:33], v[14:15], v[14:15]
	v_pk_mul_f32 v[34:35], v[12:13], v[12:13]
	v_pk_fma_f32 v[2:3], v[66:67], 0, v[36:37] op_sel_hi:[1,0,1]
	v_pk_mov_b32 v[36:37], v[34:35], v[32:33] op_sel:[1,0]
	v_mov_b32_e32 v35, v33
	v_pk_add_f32 v[32:33], v[36:37], v[34:35]
	v_pk_mul_f32 v[34:35], v[10:11], v[10:11]
	v_pk_mul_f32 v[36:37], v[8:9], v[8:9]
	v_pk_fma_f32 v[0:1], v[64:65], 0, v[38:39] op_sel_hi:[1,0,1]
	v_pk_mov_b32 v[38:39], v[36:37], v[34:35] op_sel:[1,0]
	v_mov_b32_e32 v37, v35
	v_pk_add_f32 v[34:35], v[38:39], v[36:37]
	global_store_dwordx4 v[22:23], v[12:15], off
	global_store_dwordx4 v[22:23], v[8:11], off offset:1024
	global_store_dwordx4 v[22:23], v[4:7], off offset:2048
	global_store_dwordx4 v[22:23], v[0:3], off offset:3072
	v_mul_f32_e32 v31, v0, v0
	v_mul_f32_e32 v36, v1, v1
	v_pk_add_f32 v[22:23], v[32:33], v[32:33] op_sel:[0,1] op_sel_hi:[1,0]
	v_pk_add_f32 v[32:33], v[34:35], v[34:35] op_sel:[0,1] op_sel_hi:[1,0]
	v_mov_b32_e32 v23, v31
	v_mov_b32_e32 v33, v36
	v_pk_add_f32 v[22:23], v[22:23], v[32:33]
	v_mul_f32_e32 v32, v5, v5
	v_mul_f32_e32 v34, v7, v7
	v_mul_f32_e32 v37, v2, v2
	v_mul_f32_e32 v38, v3, v3
	v_pk_fma_f32 v[32:33], v[4:5], v[4:5], v[32:33] op_sel_hi:[1,1,0]
	v_pk_fma_f32 v[34:35], v[6:7], v[6:7], v[34:35] op_sel_hi:[1,1,0]
	v_mov_b32_e32 v33, v37
	v_mov_b32_e32 v35, v38
	v_pk_add_f32 v[32:33], v[32:33], v[34:35]
	s_nop 0
	v_pk_add_f32 v[22:23], v[22:23], v[32:33]
	v_add_f32_e32 v22, v22, v23
	s_waitcnt lgkmcnt(0)
	s_nop 1
	v_add_f32_dpp v22, v22, v22 quad_perm:[1,0,3,2] row_mask:0xf bank_mask:0xf
	s_waitcnt lgkmcnt(0)
	s_nop 1
	v_add_f32_dpp v22, v22, v22 quad_perm:[2,3,0,1] row_mask:0xf bank_mask:0xf
	s_waitcnt lgkmcnt(0)
	s_nop 1
	v_add_f32_dpp v22, v22, v22 row_half_mirror row_mask:0xf bank_mask:0xf
	s_waitcnt lgkmcnt(0)
	s_nop 1
	v_add_f32_dpp v22, v22, v22 row_mirror row_mask:0xf bank_mask:0xf
	v_mov_b32_e32 v23, v22
	s_waitcnt lgkmcnt(0)
	s_nop 1
	v_permlane16_swap_b32_e32 v23, v22
	v_add_f32_e32 v22, v22, v23
	v_mov_b32_e32 v23, v22
	s_waitcnt lgkmcnt(0)
	s_nop 1
	v_permlane32_swap_b32_e32 v23, v22
	v_add_f32_e32 v22, v22, v23
	v_fmamk_f32 v22, v22, 0x3a800000, v30
	v_cmp_gt_f32_e32 vcc, s6, v22
	v_mul_f32_e32 v23, 0x4b800000, v22
	s_add_i32 s6, s8, 0x4000
	v_cndmask_b32_e32 v22, v22, v23, vcc
	v_rsq_f32_e32 v22, v22
	s_ashr_i32 s7, s6, 31
	s_lshl_b64 s[6:7], s[6:7], 11
	s_add_i32 s8, s8, s56
	v_mul_f32_e32 v23, 0x45800000, v22
	v_cndmask_b32_e32 v31, v22, v23, vcc
	v_mul_f32_e32 v12, v12, v31
	v_mul_f32_e32 v13, v13, v31
	v_lshl_add_u64 v[22:23], v[16:17], 0, s[6:7]
	v_mul_f32_e32 v8, v8, v31
	v_mul_f32_e32 v9, v9, v31
	v_mul_f32_e32 v4, v4, v31
	v_mul_f32_e32 v5, v5, v31
	s_add_u32 s0, s0, s2
	v_mul_f32_e32 v0, v0, v31
	v_mul_f32_e32 v1, v1, v31
	s_addc_u32 s1, s1, s3
	s_add_u32 s4, s4, s2
	s_addc_u32 s5, s5, s3
	s_cmpk_lt_i32 s8, 0x200
	v_mul_f32_e32 v12, v100, v12
	v_mul_f32_e32 v13, v101, v13
	v_cvt_pk_bf16_f32 v12, v12, v13
	v_mul_f32_e32 v13, v14, v31
	v_mul_f32_e32 v13, v102, v13
	v_mul_f32_e32 v14, v15, v31
	v_mul_f32_e32 v14, v103, v14
	v_cvt_pk_bf16_f32 v13, v13, v14
	global_store_dwordx2 v[22:23], v[12:13], off
	v_mul_f32_e32 v8, v104, v8
	v_mul_f32_e32 v9, v105, v9
	v_cvt_pk_bf16_f32 v8, v8, v9
	v_mul_f32_e32 v9, v10, v31
	v_mul_f32_e32 v9, v106, v9
	v_mul_f32_e32 v10, v11, v31
	v_mul_f32_e32 v10, v107, v10
	v_cvt_pk_bf16_f32 v9, v9, v10
	global_store_dwordx2 v[22:23], v[8:9], off offset:512
	v_mul_f32_e32 v4, v4, v108
	v_mul_f32_e32 v5, v5, v109
	v_cvt_pk_bf16_f32 v4, v4, v5
	v_mul_f32_e32 v5, v6, v31
	v_mul_f32_e32 v5, v5, v110
	v_mul_f32_e32 v6, v7, v31
	v_mul_f32_e32 v6, v6, v111
	v_cvt_pk_bf16_f32 v5, v5, v6
	global_store_dwordx2 v[22:23], v[4:5], off offset:1024
	v_mul_f32_e32 v0, v0, v112
	v_mul_f32_e32 v1, v1, v113
	v_cvt_pk_bf16_f32 v0, v0, v1
	v_mul_f32_e32 v1, v2, v31
	v_mul_f32_e32 v1, v1, v114
	v_mul_f32_e32 v2, v3, v31
	v_mul_f32_e32 v2, v2, v115
	v_cvt_pk_bf16_f32 v1, v1, v2
	global_store_dwordx2 v[22:23], v[0:1], off offset:1536
	s_cbranch_scc1 .LBB0_564

.LBB0_1132:
	s_andn2_b64 vcc, exec, s[0:1]
	s_cbranch_vccnz .LBB0_1182
	s_add_i32 s4, s44, 0xffffff40
	s_mul_i32 s0, s4, 0x40002
	s_lshr_b32 s0, s0, 20
	s_mul_i32 s16, s4, 6
	s_mul_i32 s0, s0, 24
	s_lshr_b32 s8, s4, 2
	s_sub_i32 s0, s16, s0
	s_waitcnt vmcnt(0)
	v_mov_b32_e32 v16, v185
	s_and_b32 s2, s0, 0xfffe
	s_mul_i32 s8, s8, 24
	s_lshl_b32 s3, s2, 2
	v_ashrrev_i32_e32 v190, 3, v16
	s_add_i32 s1, s8, s2
	v_readlane_b32 s60, v252, 0
	v_mov_b32_e32 v4, s3
	s_lshl_b32 s80, s1, 6
	v_ashrrev_i32_e32 v191, 31, v190
	v_readlane_b32 s64, v252, 4
	v_readlane_b32 s65, v252, 5
	global_load_dword v204, v4, s[38:39]
	global_load_dword v170, v4, s[36:37]
	global_load_dword v169, v4, s[40:41]
	v_lshl_add_u64 v[4:5], v[190:191], 0, s[80:81]
	v_readlane_b32 s66, v252, 6
	v_readlane_b32 s67, v252, 7
	v_readlane_b32 s68, v252, 8
	v_readlane_b32 s69, v252, 9
	s_mov_b64 s[20:21], s[64:65]
	v_and_b32_e32 v168, 7, v16
	s_mul_i32 s0, s0, 43
	v_lshlrev_b64 v[166:167], 9, v[4:5]
	s_mov_b64 s[22:23], s[66:67]
	s_mov_b64 s[24:25], s[68:69]
	v_lshl_add_u64 v[4:5], s[24:25], 0, v[166:167]
	v_lshlrev_b32_e32 v186, 6, v168
	s_and_b32 s5, s4, 0x1fc
	s_and_b32 s0, s0, 0x700
	v_readlane_b32 s22, v251, 47
	v_lshl_add_u64 v[4:5], v[4:5], 0, v[186:187]
	v_readlane_b32 s23, v251, 48
	s_add_u32 s0, s22, s0
	global_load_dwordx4 v[132:135], v[4:5], off offset:48
	global_load_dwordx4 v[136:139], v[4:5], off offset:32
	global_load_dwordx4 v[140:143], v[4:5], off offset:16
	global_load_dwordx4 v[148:151], v[4:5], off
	s_addc_u32 s1, s23, 0
	v_lshlrev_b32_e32 v4, 5, v168
	v_mov_b32_e32 v5, v187
	v_lshl_add_u64 v[6:7], s[0:1], 0, v[4:5]
	s_add_u32 s0, s42, s3
	s_addc_u32 s1, s43, 0
	s_lshl_b32 s17, s2, 6
	s_lshl_b32 s2, s2, 7
	v_readlane_b32 s26, v251, 50
	v_and_b32_e32 v8, -2, v190
	v_readlane_b32 s27, v251, 51
	s_add_u32 s2, s26, s2
	v_ashrrev_i32_e32 v9, 31, v8
	s_addc_u32 s3, s27, 0
	v_lshlrev_b64 v[12:13], 1, v[8:9]
	v_lshl_add_u64 v[8:9], s[2:3], 0, v[12:13]
	s_or_b32 s2, s5, 0x4000
	s_lshl_b32 s80, s2, 11
	s_mulk_i32 s2, 0x60
	v_mov_b32_e32 v17, s2
	global_load_dword v205, v17, s[0:1]
	s_mul_i32 s19, s5, 0x600
	s_lshl_b32 s10, s19, 1
	s_mov_b32 s11, s81
	v_lshl_add_u64 v[14:15], v[8:9], 0, s[10:11]
	v_lshl_add_u64 v[10:11], v[6:7], 0, s[80:81]
	global_load_dword v189, v[14:15], off
	global_load_dwordx4 v[144:147], v[10:11], off offset:16
	global_load_dwordx4 v[156:159], v[10:11], off
	global_load_dwordx4 v[152:155], v[10:11], off offset:1040
	global_load_dwordx4 v[160:163], v[10:11], off offset:1024
	s_or_b32 s2, s5, 0x4001
	s_lshl_b32 s12, s2, 11
	s_mulk_i32 s2, 0x60
	v_mov_b32_e32 v18, s2
	s_or_b32 s2, s5, 0x4002
	s_mov_b32 s13, s81
	s_lshl_b32 s14, s2, 11
	s_mulk_i32 s2, 0x60
	s_or_b32 s6, s4, 3
	s_or_b32 s4, s4, 0x4003
	s_mov_b32 s5, s81
	v_lshl_add_u64 v[10:11], v[6:7], 0, s[12:13]
	global_load_dword v207, v18, s[0:1]
	global_load_dword v179, v[14:15], off offset:3072
	global_load_dwordx4 v[104:107], v[10:11], off offset:16
	global_load_dwordx4 v[120:123], v[10:11], off
	global_load_dwordx4 v[116:119], v[10:11], off offset:1040
	global_load_dwordx4 v[128:131], v[10:11], off offset:1024
	v_mov_b32_e32 v19, s2
	v_add_co_u32_e32 v14, vcc, s78, v14
	s_lshl_b64 s[2:3], s[4:5], 11
	s_mul_i32 s20, s4, 0x60
	global_load_dword v178, v19, s[0:1]
	v_addc_co_u32_e32 v15, vcc, 0, v15, vcc
	s_mul_hi_u32 s18, s4, 0x60
	s_add_u32 s0, s0, s20
	v_lshl_add_u64 v[194:195], s[22:23], 0, v[4:5]
	v_and_b32_e32 v4, 8, v16
	v_and_b32_e32 v5, 64, v198
	s_mov_b32 s15, s81
	s_addc_u32 s1, s1, s18
	v_cmp_eq_u32_e32 vcc, 0, v4
	v_xor_b32_e32 v4, 1, v198
	v_add_u32_e32 v188, 64, v5
	v_lshl_add_u64 v[10:11], v[6:7], 0, s[14:15]
	global_load_dword v177, v[14:15], off offset:2048
	global_load_dwordx4 v[52:55], v[10:11], off offset:16
	global_load_dwordx4 v[68:71], v[10:11], off
	global_load_dwordx4 v[60:63], v[10:11], off offset:1040
	global_load_dwordx4 v[84:87], v[10:11], off offset:1024
	global_load_dword v176, v187, s[0:1]
	v_cmp_lt_i32_e64 s[0:1], v4, v188
	s_mul_i32 s4, s6, 0x600
	s_lshl_b64 s[6:7], s[4:5], 1
	v_cndmask_b32_e64 v4, v198, v4, s[0:1]
	s_or_b32 s0, s16, 1
	s_and_b32 s1, s0, 0xffff
	s_mul_i32 s1, s1, 0xaaab
	s_lshr_b32 s1, s1, 20
	s_mul_i32 s1, s1, 24
	s_sub_i32 s0, s0, s1
	s_and_b32 s5, s0, 0xffff
	s_add_i32 s8, s8, s5
	s_mul_i32 s9, s0, 43
	s_lshl_b32 s21, s5, 2
	s_lshl_b32 s0, s8, 6
	s_mov_b32 s1, s81
	v_lshl_add_u64 v[8:9], v[8:9], 0, s[6:7]
	v_lshlrev_b32_e32 v203, 2, v4
	v_mov_b32_e32 v4, s21
	v_lshl_add_u64 v[164:165], v[190:191], 0, s[0:1]
	v_lshl_add_u64 v[6:7], v[6:7], 0, s[2:3]
	global_load_dword v171, v[8:9], off
	s_nop 0
	global_load_dwordx4 v[8:11], v[6:7], off offset:16
	global_load_dwordx4 v[28:31], v[6:7], off
	global_load_dwordx4 v[24:27], v[6:7], off offset:1040
	global_load_dwordx4 v[36:39], v[6:7], off offset:1024
	global_load_dword v197, v4, s[38:39]
	global_load_dword v173, v4, s[36:37]
	global_load_dword v172, v4, s[40:41]
	v_lshlrev_b64 v[4:5], 9, v[164:165]
	v_lshl_add_u64 v[4:5], s[24:25], 0, v[4:5]
	s_and_b32 s0, s9, 0x700
	v_lshl_add_u64 v[4:5], v[4:5], 0, v[186:187]
	s_add_u32 s8, s42, s21
	v_lshl_add_u64 v[192:193], s[26:27], 0, v[12:13]
	global_load_dwordx4 v[76:79], v[4:5], off offset:48
	global_load_dwordx4 v[80:83], v[4:5], off offset:32
	global_load_dwordx4 v[96:99], v[4:5], off offset:16
	global_load_dwordx4 v[100:103], v[4:5], off
	v_lshl_add_u64 v[4:5], v[194:195], 0, s[0:1]
	s_addc_u32 s9, s43, 0
	s_lshl_b32 s0, s5, 7
	v_lshl_add_u64 v[6:7], v[192:193], 0, s[0:1]
	v_lshl_add_u64 v[12:13], v[4:5], 0, s[80:81]
	v_lshl_add_u64 v[14:15], v[6:7], 0, s[10:11]
	global_load_dword v206, v17, s[8:9]
	global_load_dword v196, v[14:15], off
	global_load_dwordx4 v[92:95], v[12:13], off offset:16
	global_load_dwordx4 v[112:115], v[12:13], off
	global_load_dwordx4 v[108:111], v[12:13], off offset:1040
	global_load_dwordx4 v[124:127], v[12:13], off offset:1024
	v_lshl_add_u64 v[12:13], v[4:5], 0, s[12:13]
	global_load_dword v183, v18, s[8:9]
	global_load_dword v181, v[14:15], off offset:3072
	global_load_dwordx4 v[32:35], v[12:13], off offset:16
	global_load_dwordx4 v[44:47], v[12:13], off
	global_load_dwordx4 v[40:43], v[12:13], off offset:1040
	global_load_dwordx4 v[56:59], v[12:13], off offset:1024
	v_add_co_u32_e64 v14, s[0:1], s78, v14
	v_lshl_add_u64 v[12:13], v[4:5], 0, s[14:15]
	s_nop 0
	v_addc_co_u32_e64 v15, s[0:1], 0, v15, s[0:1]
	s_add_u32 s0, s8, s20
	v_lshl_add_u64 v[20:21], v[4:5], 0, s[2:3]
	s_addc_u32 s1, s9, s18
	v_lshl_add_u64 v[4:5], v[6:7], 0, s[6:7]
	global_load_dword v175, v19, s[8:9]
	global_load_dword v182, v[14:15], off offset:2048
	global_load_dwordx4 v[48:51], v[12:13], off offset:16
	global_load_dwordx4 v[72:75], v[12:13], off
	global_load_dwordx4 v[64:67], v[12:13], off offset:1040
	global_load_dwordx4 v[88:91], v[12:13], off offset:1024
	global_load_dword v180, v187, s[0:1]
	global_load_dword v174, v[4:5], off
	s_nop 0
	global_load_dwordx4 v[4:7], v[20:21], off offset:16
	global_load_dwordx4 v[16:19], v[20:21], off
	global_load_dwordx4 v[12:15], v[20:21], off offset:1040
	s_nop 0
	global_load_dwordx4 v[20:23], v[20:21], off offset:1024
	s_waitcnt vmcnt(31)
	v_add_f32_e32 v205, v170, v205
	v_mul_f32_e64 v186, |v205|, s33
	v_exp_f32_e32 v208, v186
	s_or_b32 s8, s17, 0x1800000
	v_mul_f32_e32 v186, 0x3fb8aa3b, v204
	v_exp_f32_e32 v186, v186
	v_add_f32_e32 v209, 1.0, v208
	v_cmp_gt_f32_e64 s[0:1], s58, v209
	s_and_b64 s[2:3], s[0:1], exec
	s_cselect_b32 s2, 32, 0
	v_ldexp_f32 v209, v209, s2
	v_log_f32_e32 v209, v209
	v_fmamk_f32 v204, v208, 0xbe800000, v199
	v_fma_f32 v204, -v208, v204, 0.5
	v_fma_f32 v204, -v208, v204, 1.0
	v_mul_f32_e32 v210, 0x3f317217, v209
	v_fma_f32 v210, v209, s59, -v210
	v_fmac_f32_e32 v210, 0x3377d1cf, v209
	v_fmac_f32_e32 v210, 0x3f317217, v209
	v_cmp_lt_f32_e64 s[2:3], |v209|, s96
	v_mul_f32_e32 v204, v208, v204
	v_max_f32_e32 v205, 0, v205
	v_cndmask_b32_e64 v209, v209, v210, s[2:3]
	v_cndmask_b32_e64 v210, 0, v201, s[0:1]
	v_sub_f32_e32 v209, v209, v210
	v_cmp_gt_f32_e64 s[0:1], s97, v208
	v_and_b32_e32 v208, 0xffff0000, v189
	v_lshlrev_b32_e32 v189, 16, v189
	v_cndmask_b32_e64 v204, v209, v204, s[0:1]
	v_add_f32_e32 v205, v205, v204
	v_mul_f32_e32 v204, v205, v186
	v_mul_f32_e32 v204, 0xbfb8aa3b, v204
	v_exp_f32_e32 v204, v204
	v_cndmask_b32_e32 v208, v208, v189, vcc
	v_mul_f32_e32 v210, v205, v208
	v_and_b32_e32 v205, 0xffff0000, v160
	v_lshlrev_b32_e32 v189, 16, v160
	v_lshlrev_b32_e32 v209, 16, v161
	v_and_b32_e32 v211, 0xffff0000, v161
	v_lshlrev_b32_e32 v160, 16, v156
	v_and_b32_e32 v161, 0xffff0000, v156
	v_pk_mul_f32 v[148:149], v[148:149], v[204:205] op_sel_hi:[1,0]
	v_lshlrev_b32_e32 v156, 16, v157
	v_pk_fma_f32 v[148:149], v[210:211], v[160:161], v[148:149] op_sel_hi:[0,1,1]
	v_fma_f32 v160, v148, v189, 0
	v_and_b32_e32 v157, 0xffff0000, v157
	v_pk_mul_f32 v[150:151], v[150:151], v[204:205] op_sel_hi:[1,0]
	v_fmac_f32_e32 v160, v149, v205
	v_pk_fma_f32 v[150:151], v[210:211], v[156:157], v[150:151] op_sel_hi:[0,1,1]
	v_fmac_f32_e32 v160, v150, v209
	v_lshlrev_b32_e32 v156, 16, v158
	v_and_b32_e32 v157, 0xffff0000, v158
	v_pk_mul_f32 v[140:141], v[140:141], v[204:205] op_sel_hi:[1,0]
	v_lshlrev_b32_e32 v212, 16, v162
	v_fmac_f32_e32 v160, v151, v211
	v_pk_fma_f32 v[140:141], v[210:211], v[156:157], v[140:141] op_sel_hi:[0,1,1]
	v_and_b32_e32 v162, 0xffff0000, v162
	v_fmac_f32_e32 v160, v140, v212
	v_lshlrev_b32_e32 v156, 16, v159
	v_and_b32_e32 v157, 0xffff0000, v159
	v_pk_mul_f32 v[142:143], v[142:143], v[204:205] op_sel_hi:[1,0]
	v_lshlrev_b32_e32 v213, 16, v163
	v_fmac_f32_e32 v160, v141, v162
	v_pk_fma_f32 v[142:143], v[210:211], v[156:157], v[142:143] op_sel_hi:[0,1,1]
	v_and_b32_e32 v163, 0xffff0000, v163
	v_fmac_f32_e32 v160, v142, v213
	v_lshlrev_b32_e32 v156, 16, v152
	v_and_b32_e32 v157, 0xffff0000, v152
	v_lshlrev_b32_e32 v158, 16, v153
	v_and_b32_e32 v159, 0xffff0000, v153
	v_lshlrev_b32_e32 v152, 16, v144
	v_and_b32_e32 v153, 0xffff0000, v144
	v_pk_mul_f32 v[136:137], v[136:137], v[204:205] op_sel_hi:[1,0]
	v_fmac_f32_e32 v160, v143, v163
	v_pk_fma_f32 v[136:137], v[210:211], v[152:153], v[136:137] op_sel_hi:[0,1,1]
	v_fmac_f32_e32 v160, v136, v156
	v_lshlrev_b32_e32 v144, 16, v145
	v_and_b32_e32 v145, 0xffff0000, v145
	v_pk_mul_f32 v[138:139], v[138:139], v[204:205] op_sel_hi:[1,0]
	v_fmac_f32_e32 v160, v137, v157
	v_pk_fma_f32 v[138:139], v[210:211], v[144:145], v[138:139] op_sel_hi:[0,1,1]
	v_fmac_f32_e32 v160, v138, v158
	v_lshlrev_b32_e32 v144, 16, v146
	v_and_b32_e32 v145, 0xffff0000, v146
	v_pk_mul_f32 v[132:133], v[132:133], v[204:205] op_sel_hi:[1,0]
	v_lshlrev_b32_e32 v161, 16, v154
	v_fmac_f32_e32 v160, v139, v159
	v_pk_fma_f32 v[132:133], v[210:211], v[144:145], v[132:133] op_sel_hi:[0,1,1]
	v_and_b32_e32 v154, 0xffff0000, v154
	v_fmac_f32_e32 v160, v132, v161
	v_lshlrev_b32_e32 v144, 16, v147
	v_and_b32_e32 v145, 0xffff0000, v147
	v_pk_mul_f32 v[134:135], v[134:135], v[204:205] op_sel_hi:[1,0]
	v_lshlrev_b32_e32 v162, 16, v155
	v_fmac_f32_e32 v160, v133, v154
	v_pk_fma_f32 v[134:135], v[210:211], v[144:145], v[134:135] op_sel_hi:[0,1,1]
	v_and_b32_e32 v155, 0xffff0000, v155
	v_fmac_f32_e32 v160, v134, v162
	v_fmac_f32_e32 v160, v135, v155
	ds_bpermute_b32 v144, v203, v160
	v_xor_b32_e32 v145, 2, v198
	v_cmp_lt_i32_e64 s[0:1], v145, v188
	v_xor_b32_e32 v146, 4, v198
	v_cmp_eq_u32_e64 s[6:7], 0, v168
	v_cndmask_b32_e64 v145, v198, v145, s[0:1]
	v_lshlrev_b32_e32 v204, 2, v145
	s_waitcnt lgkmcnt(0)
	v_add_f32_e32 v144, v160, v144
	ds_bpermute_b32 v145, v204, v144
	v_cmp_lt_i32_e64 s[0:1], v146, v188
	v_readlane_b32 s61, v252, 1
	v_readlane_b32 s62, v252, 2
	v_cndmask_b32_e64 v146, v198, v146, s[0:1]
	v_lshlrev_b32_e32 v205, 2, v146
	s_waitcnt lgkmcnt(0)
	v_add_f32_e32 v144, v144, v145
	ds_bpermute_b32 v145, v205, v144
	v_readlane_b32 s0, v251, 56
	v_readlane_b32 s1, v251, 57
	v_readlane_b32 s63, v252, 3
	v_readlane_b32 s70, v252, 10
	v_lshl_add_u64 v[188:189], v[190:191], 1, s[0:1]
	v_readlane_b32 s71, v252, 11
	v_readlane_b32 s72, v252, 12
	v_readlane_b32 s73, v252, 13
	v_readlane_b32 s74, v252, 14
	v_readlane_b32 s75, v252, 15
	s_and_saveexec_b64 s[0:1], s[6:7]
	s_cbranch_execz .LBB0_1135
	s_or_b32 s2, s8, s19
	s_lshl_b32 s80, s2, 1
	s_waitcnt lgkmcnt(0)
	v_add_f32_e32 v144, v144, v145
	v_lshl_add_u64 v[146:147], v[188:189], 0, s[80:81]
	v_fmac_f32_e32 v144, v169, v208
	v_cvt_pk_bf16_f32 v144, v144, v187
	global_store_short v[146:147], v144, off

.LBB0_1141:
	s_or_b64 exec, exec, s[0:1]
	s_add_i32 s22, s16, 2
	s_and_b32 s0, s22, 0xffff
	s_mul_i32 s0, s0, 0xaaab
	s_lshr_b32 s17, s0, 20
	s_mul_i32 s5, s17, 24
	v_lshlrev_b32_e32 v54, 4, v168
	s_sub_i32 s0, s22, s5
	s_waitcnt lgkmcnt(0)
	v_lshl_add_u64 v[52:53], s[56:57], 0, v[166:167]
	v_lshlrev_b32_e32 v186, 2, v54
	s_and_b32 s18, s0, 0xffff
	v_lshl_add_u64 v[52:53], v[52:53], 0, v[186:187]
	s_lshl_b32 s3, s18, 2
	global_store_dwordx4 v[52:53], v[36:39], off
	global_store_dwordx4 v[52:53], v[28:31], off offset:16
	global_store_dwordx4 v[52:53], v[24:27], off offset:32
	global_store_dwordx4 v[52:53], v[8:11], off offset:48
	s_mul_i32 s1, s0, 0xab
	s_lshl_b32 s80, s22, 6
	v_mov_b32_e32 v8, s3
	global_load_dword v224, v8, s[38:39]
	global_load_dword v208, v8, s[36:37]
	global_load_dword v207, v8, s[40:41]
	v_lshl_add_u64 v[8:9], v[190:191], 0, s[80:81]
	v_readlane_b32 s60, v252, 0
	s_lshr_b32 s1, s1, 2
	v_lshlrev_b64 v[8:9], 9, v[8:9]
	v_readlane_b32 s68, v252, 8
	v_readlane_b32 s69, v252, 9
	s_lshl_b32 s8, s17, 2
	s_and_b32 s80, s1, 0x3f00
	v_lshl_add_u64 v[8:9], s[68:69], 0, v[8:9]
	s_add_u32 s28, s42, s3
	v_lshl_add_u64 v[8:9], v[8:9], 0, v[186:187]
	s_addc_u32 s29, s43, 0
	s_lshl_b32 s0, s0, 7
	global_load_dwordx4 v[132:135], v[8:9], off offset:48
	global_load_dwordx4 v[136:139], v[8:9], off offset:32
	global_load_dwordx4 v[144:147], v[8:9], off offset:16
	global_load_dwordx4 v[152:155], v[8:9], off
	v_lshl_add_u64 v[8:9], v[194:195], 0, s[80:81]
	s_and_b32 s80, s0, 0x1ff80
	s_or_b32 s24, s8, 0x4000
	v_lshl_add_u64 v[10:11], v[192:193], 0, s[80:81]
	s_lshl_b32 s80, s24, 11
	s_mulk_i32 s24, 0x60
	s_mulk_i32 s17, 0x1800
	s_or_b32 s25, s8, 0x4001
	v_mov_b32_e32 v26, s24
	s_lshl_b32 s10, s17, 1
	s_mov_b32 s11, s81
	s_lshl_b32 s12, s25, 11
	s_mulk_i32 s25, 0x60
	s_or_b32 s26, s8, 0x4002
	v_lshl_add_u64 v[24:25], v[8:9], 0, s[80:81]
	global_load_dword v226, v26, s[28:29]
	v_lshl_add_u64 v[10:11], v[10:11], 0, s[10:11]
	s_mov_b32 s13, s81
	v_mov_b32_e32 v26, s25
	s_lshl_b32 s14, s26, 11
	s_mulk_i32 s26, 0x60
	global_load_dword v222, v[10:11], off
	global_load_dwordx4 v[140:143], v[24:25], off offset:16
	global_load_dwordx4 v[168:171], v[24:25], off
	global_load_dwordx4 v[156:159], v[24:25], off offset:1040
	global_load_dwordx4 v[176:179], v[24:25], off offset:1024
	v_lshl_add_u64 v[24:25], v[8:9], 0, s[12:13]
	global_load_dword v220, v26, s[28:29]
	global_load_dword v219, v[10:11], off offset:3072
	global_load_dwordx4 v[104:107], v[24:25], off offset:16
	global_load_dwordx4 v[120:123], v[24:25], off
	global_load_dwordx4 v[116:119], v[24:25], off offset:1040
	global_load_dwordx4 v[128:131], v[24:25], off offset:1024
	v_mov_b32_e32 v26, s26
	s_or_b32 s23, s8, 0x4003
	s_mov_b32 s15, s81
	global_load_dword v217, v26, s[28:29]
	v_add_co_u32_e64 v26, s[0:1], s78, v10
	s_lshl_b32 s8, s23, 11
	s_mov_b32 s9, s81
	s_mulk_i32 s23, 0x60
	v_lshl_add_u64 v[24:25], v[8:9], 0, s[14:15]
	v_addc_co_u32_e64 v27, s[0:1], 0, v11, s[0:1]
	v_lshl_add_u64 v[36:37], v[8:9], 0, s[8:9]
	v_mov_b32_e32 v8, s23
	global_load_dword v215, v[26:27], off offset:2048
	global_load_dwordx4 v[52:55], v[24:25], off offset:16
	global_load_dwordx4 v[68:71], v[24:25], off
	global_load_dwordx4 v[60:63], v[24:25], off offset:1040
	global_load_dwordx4 v[84:87], v[24:25], off offset:1024
	global_load_dword v212, v8, s[28:29]
	v_add_co_u32_e64 v8, s[0:1], s79, v10
	s_waitcnt vmcnt(30)
	v_add_f32_e32 v149, v173, v206
	s_nop 0
	v_addc_co_u32_e64 v9, s[0:1], 0, v11, s[0:1]
	global_load_dword v210, v[8:9], off offset:1024
	s_nop 0
	global_load_dwordx4 v[8:11], v[36:37], off offset:16
	global_load_dwordx4 v[28:31], v[36:37], off
	global_load_dwordx4 v[24:27], v[36:37], off offset:1040
	s_nop 0
	global_load_dwordx4 v[36:39], v[36:37], off offset:1024
	v_mul_f32_e64 v150, |v149|, s33
	v_exp_f32_e32 v150, v150
	s_or_b32 s11, s2, 0x1800000
	v_mul_f32_e32 v148, 0x3fb8aa3b, v197
	v_exp_f32_e32 v148, v148
	v_add_f32_e32 v160, 1.0, v150
	v_cmp_gt_f32_e64 s[0:1], s58, v160
	s_and_b64 s[2:3], s[0:1], exec
	s_cselect_b32 s2, 32, 0
	v_ldexp_f32 v160, v160, s2
	v_log_f32_e32 v160, v160
	v_fmamk_f32 v151, v150, 0xbe800000, v199
	v_fma_f32 v151, -v150, v151, 0.5
	v_fma_f32 v151, -v150, v151, 1.0
	v_mul_f32_e32 v161, 0x3f317217, v160
	v_fma_f32 v161, v160, s59, -v161
	v_fmac_f32_e32 v161, 0x3377d1cf, v160
	v_fmac_f32_e32 v161, 0x3f317217, v160
	v_cmp_lt_f32_e64 s[2:3], |v160|, s96
	v_mul_f32_e32 v151, v150, v151
	v_max_f32_e32 v149, 0, v149
	v_cndmask_b32_e64 v160, v160, v161, s[2:3]
	v_cndmask_b32_e64 v161, 0, v201, s[0:1]
	v_sub_f32_e32 v160, v160, v161
	v_cmp_gt_f32_e64 s[0:1], s97, v150
	v_and_b32_e32 v161, 0xffff0000, v124
	v_lshlrev_b32_e32 v162, 16, v125
	v_cndmask_b32_e64 v150, v160, v151, s[0:1]
	v_add_f32_e32 v151, v149, v150
	v_mul_f32_e32 v149, v151, v148
	v_mul_f32_e32 v149, 0xbfb8aa3b, v149
	v_exp_f32_e32 v150, v149
	v_and_b32_e32 v149, 0xffff0000, v196
	v_lshlrev_b32_e32 v160, 16, v196
	v_cndmask_b32_e32 v149, v149, v160, vcc
	v_mul_f32_e32 v160, v151, v149
	v_lshlrev_b32_e32 v151, 16, v124
	v_and_b32_e32 v163, 0xffff0000, v125
	v_lshlrev_b32_e32 v124, 16, v112
	v_and_b32_e32 v125, 0xffff0000, v112
	v_pk_mul_f32 v[100:101], v[100:101], v[150:151] op_sel_hi:[1,0]
	v_lshlrev_b32_e32 v112, 16, v113
	v_pk_fma_f32 v[100:101], v[160:161], v[124:125], v[100:101] op_sel_hi:[0,1,1]
	v_fma_f32 v124, v100, v151, 0
	v_and_b32_e32 v113, 0xffff0000, v113
	v_pk_mul_f32 v[102:103], v[102:103], v[150:151] op_sel_hi:[1,0]
	v_fmac_f32_e32 v124, v101, v161
	v_pk_fma_f32 v[102:103], v[160:161], v[112:113], v[102:103] op_sel_hi:[0,1,1]
	v_fmac_f32_e32 v124, v102, v162
	v_lshlrev_b32_e32 v112, 16, v114
	v_and_b32_e32 v113, 0xffff0000, v114
	v_pk_mul_f32 v[96:97], v[96:97], v[150:151] op_sel_hi:[1,0]
	v_lshlrev_b32_e32 v166, 16, v126
	v_fmac_f32_e32 v124, v103, v163
	v_pk_fma_f32 v[96:97], v[160:161], v[112:113], v[96:97] op_sel_hi:[0,1,1]
	v_and_b32_e32 v126, 0xffff0000, v126
	v_fmac_f32_e32 v124, v96, v166
	v_lshlrev_b32_e32 v112, 16, v115
	v_and_b32_e32 v113, 0xffff0000, v115
	v_pk_mul_f32 v[98:99], v[98:99], v[150:151] op_sel_hi:[1,0]
	v_lshlrev_b32_e32 v167, 16, v127
	v_fmac_f32_e32 v124, v97, v126
	v_pk_fma_f32 v[98:99], v[160:161], v[112:113], v[98:99] op_sel_hi:[0,1,1]
	v_and_b32_e32 v127, 0xffff0000, v127
	v_fmac_f32_e32 v124, v98, v167
	v_lshlrev_b32_e32 v112, 16, v108
	v_and_b32_e32 v113, 0xffff0000, v108
	v_lshlrev_b32_e32 v114, 16, v109
	v_and_b32_e32 v115, 0xffff0000, v109
	v_lshlrev_b32_e32 v108, 16, v92
	v_and_b32_e32 v109, 0xffff0000, v92
	v_pk_mul_f32 v[80:81], v[80:81], v[150:151] op_sel_hi:[1,0]
	v_fmac_f32_e32 v124, v99, v127
	v_pk_fma_f32 v[80:81], v[160:161], v[108:109], v[80:81] op_sel_hi:[0,1,1]
	v_fmac_f32_e32 v124, v80, v112
	v_lshlrev_b32_e32 v92, 16, v93
	v_and_b32_e32 v93, 0xffff0000, v93
	v_pk_mul_f32 v[82:83], v[82:83], v[150:151] op_sel_hi:[1,0]
	v_fmac_f32_e32 v124, v81, v113
	v_pk_fma_f32 v[82:83], v[160:161], v[92:93], v[82:83] op_sel_hi:[0,1,1]
	v_fmac_f32_e32 v124, v82, v114
	v_lshlrev_b32_e32 v92, 16, v94
	v_and_b32_e32 v93, 0xffff0000, v94
	v_pk_mul_f32 v[76:77], v[76:77], v[150:151] op_sel_hi:[1,0]
	v_lshlrev_b32_e32 v125, 16, v110
	v_fmac_f32_e32 v124, v83, v115
	v_pk_fma_f32 v[76:77], v[160:161], v[92:93], v[76:77] op_sel_hi:[0,1,1]
	v_and_b32_e32 v110, 0xffff0000, v110
	v_fmac_f32_e32 v124, v76, v125
	v_lshlrev_b32_e32 v92, 16, v95
	v_and_b32_e32 v93, 0xffff0000, v95
	v_pk_mul_f32 v[78:79], v[78:79], v[150:151] op_sel_hi:[1,0]
	v_lshlrev_b32_e32 v126, 16, v111
	v_fmac_f32_e32 v124, v77, v110
	v_pk_fma_f32 v[78:79], v[160:161], v[92:93], v[78:79] op_sel_hi:[0,1,1]
	v_and_b32_e32 v111, 0xffff0000, v111
	v_fmac_f32_e32 v124, v78, v126
	v_fmac_f32_e32 v124, v79, v111
	ds_bpermute_b32 v92, v203, v124
	v_readlane_b32 s61, v252, 1
	v_readlane_b32 s62, v252, 2
	v_readlane_b32 s63, v252, 3
	v_readlane_b32 s64, v252, 4
	s_waitcnt lgkmcnt(0)
	v_add_f32_e32 v92, v124, v92
	ds_bpermute_b32 v93, v204, v92
	v_readlane_b32 s65, v252, 5
	v_readlane_b32 s66, v252, 6
	v_readlane_b32 s67, v252, 7
	v_readlane_b32 s70, v252, 10
	s_waitcnt lgkmcnt(0)
	v_add_f32_e32 v92, v92, v93
	ds_bpermute_b32 v93, v205, v92
	v_readlane_b32 s71, v252, 11
	v_readlane_b32 s72, v252, 12
	v_readlane_b32 s73, v252, 13
	v_readlane_b32 s74, v252, 14
	v_readlane_b32 s75, v252, 15
	s_and_saveexec_b64 s[0:1], s[6:7]
	s_cbranch_execz .LBB0_1143
	s_or_b32 s2, s11, s19
	s_lshl_b32 s2, s2, 1
	s_mov_b32 s3, s81
	s_waitcnt lgkmcnt(0)
	v_add_f32_e32 v92, v92, v93
	v_lshl_add_u64 v[94:95], v[188:189], 0, s[2:3]
	v_fmac_f32_e32 v92, v172, v149
	v_cvt_pk_bf16_f32 v92, v92, v187
	global_store_short v[94:95], v92, off

.LBB0_1710:
	v_add_co_u32_e32 v32, vcc, 0x1000, v82
	global_load_dwordx4 v[28:31], v[82:83], off
	global_load_dwordx4 v[24:27], v[82:83], off offset:1024
	global_load_dwordx4 v[20:23], v[82:83], off offset:2048
	global_load_dwordx4 v[16:19], v[82:83], off offset:3072
	v_addc_co_u32_e32 v33, vcc, 0, v83, vcc
	v_add_co_u32_e32 v34, vcc, 0x2000, v82
	global_load_dwordx4 v[12:15], v[78:79], off
	global_load_dwordx4 v[8:11], v[78:79], off offset:1024
	global_load_dwordx4 v[4:7], v[78:79], off offset:2048
	global_load_dwordx4 v[0:3], v[78:79], off offset:3072
	global_load_dwordx4 v[94:97], v[32:33], off
	global_load_dwordx4 v[72:75], v[32:33], off offset:1024
	global_load_dwordx4 v[64:67], v[32:33], off offset:3072
	global_load_dwordx4 v[68:71], v[32:33], off offset:2048
	v_addc_co_u32_e32 v35, vcc, 0, v83, vcc
	global_load_dwordx4 v[60:63], v[34:35], off
	global_load_dwordx4 v[56:59], v[34:35], off offset:1024
	global_load_dwordx4 v[48:51], v[34:35], off offset:3072
	global_load_dwordx4 v[52:55], v[34:35], off offset:2048
	v_add_co_u32_e32 v36, vcc, 0x3000, v82
	v_add_co_u32_e64 v84, s[0:1], s9, v80
	s_nop 0
	v_addc_co_u32_e32 v37, vcc, 0, v83, vcc
	global_load_dwordx4 v[44:47], v[36:37], off
	global_load_dwordx4 v[40:43], v[36:37], off offset:1024
	global_load_dwordx4 v[32:35], v[36:37], off offset:3072
	s_nop 0
	global_load_dwordx4 v[36:39], v[36:37], off offset:2048
	v_addc_co_u32_e64 v85, s[0:1], 0, v81, s[0:1]
	s_add_i32 s15, s15, s8
	s_cmpk_gt_i32 s15, 0x3fff
	v_lshl_add_u64 v[82:83], v[82:83], 0, s[12:13]
	s_waitcnt vmcnt(0)
	v_pk_mul_f32 v[98:99], v[30:31], v[30:31]
	v_pk_mul_f32 v[100:101], v[28:29], v[28:29]
	v_pk_mul_f32 v[102:103], v[26:27], v[26:27]
	v_pk_mul_f32 v[104:105], v[24:25], v[24:25]
	v_mul_f32_e32 v109, v18, v18
	v_mul_f32_e32 v106, v21, v21
	v_mul_f32_e32 v108, v23, v23
	v_mul_f32_e32 v112, v19, v19
	v_pk_mov_b32 v[110:111], v[100:101], v[98:99] op_sel:[1,0]
	v_mov_b32_e32 v101, v99
	v_pk_mov_b32 v[98:99], v[104:105], v[102:103] op_sel:[1,0]
	v_mov_b32_e32 v105, v103
	v_pk_fma_f32 v[102:103], v[20:21], v[20:21], v[106:107] op_sel_hi:[1,1,0]
	v_pk_fma_f32 v[106:107], v[22:23], v[22:23], v[108:109] op_sel_hi:[1,1,0]
	v_pk_add_f32 v[100:101], v[110:111], v[100:101]
	v_pk_add_f32 v[98:99], v[98:99], v[104:105]
	v_mov_b32_e32 v103, v109
	v_mov_b32_e32 v107, v112
	v_pk_mul_f32 v[104:105], v[96:97], v[96:97]
	v_pk_mul_f32 v[108:109], v[94:95], v[94:95]
	v_pk_mul_f32 v[110:111], v[74:75], v[74:75]
	v_pk_mul_f32 v[112:113], v[72:73], v[72:73]
	v_mul_f32_e32 v114, v69, v69
	v_mul_f32_e32 v116, v71, v71
	v_mul_f32_e32 v93, v16, v16
	v_mul_f32_e32 v125, v17, v17
	v_mul_f32_e32 v127, v66, v66
	v_mul_f32_e32 v128, v67, v67
	v_pk_add_f32 v[100:101], v[100:101], v[100:101] op_sel:[0,1] op_sel_hi:[1,0]
	v_pk_add_f32 v[98:99], v[98:99], v[98:99] op_sel:[0,1] op_sel_hi:[1,0]
	v_pk_add_f32 v[102:103], v[102:103], v[106:107]
	v_pk_mov_b32 v[106:107], v[108:109], v[104:105] op_sel:[1,0]
	v_mov_b32_e32 v109, v105
	v_pk_mov_b32 v[104:105], v[112:113], v[110:111] op_sel:[1,0]
	v_mov_b32_e32 v113, v111
	v_pk_fma_f32 v[110:111], v[68:69], v[68:69], v[114:115] op_sel_hi:[1,1,0]
	v_pk_fma_f32 v[114:115], v[70:71], v[70:71], v[116:117] op_sel_hi:[1,1,0]
	v_pk_mul_f32 v[116:117], v[62:63], v[62:63]
	v_pk_mul_f32 v[118:119], v[60:61], v[60:61]
	v_pk_mul_f32 v[120:121], v[58:59], v[58:59]
	v_pk_mul_f32 v[122:123], v[56:57], v[56:57]
	v_mul_f32_e32 v124, v53, v53
	v_mul_f32_e32 v126, v55, v55
	v_mov_b32_e32 v101, v93
	v_mov_b32_e32 v99, v125
	v_pk_add_f32 v[106:107], v[106:107], v[108:109]
	v_pk_add_f32 v[104:105], v[104:105], v[112:113]
	v_mov_b32_e32 v111, v127
	v_mov_b32_e32 v115, v128
	v_pk_mov_b32 v[108:109], v[118:119], v[116:117] op_sel:[1,0]
	v_mov_b32_e32 v119, v117
	v_pk_mov_b32 v[112:113], v[122:123], v[120:121] op_sel:[1,0]
	v_mov_b32_e32 v123, v121
	v_pk_fma_f32 v[116:117], v[52:53], v[52:53], v[124:125] op_sel_hi:[1,1,0]
	v_pk_fma_f32 v[120:121], v[54:55], v[54:55], v[126:127] op_sel_hi:[1,1,0]
	v_pk_mul_f32 v[124:125], v[46:47], v[46:47]
	v_pk_mul_f32 v[126:127], v[44:45], v[44:45]
	v_pk_mul_f32 v[128:129], v[42:43], v[42:43]
	v_pk_mul_f32 v[130:131], v[40:41], v[40:41]
	v_mul_f32_e32 v133, v64, v64
	v_mul_f32_e32 v135, v65, v65
	v_mul_f32_e32 v138, v50, v50
	v_mul_f32_e32 v139, v51, v51
	v_pk_add_f32 v[98:99], v[100:101], v[98:99]
	v_pk_add_f32 v[100:101], v[106:107], v[106:107] op_sel:[0,1] op_sel_hi:[1,0]
	v_pk_add_f32 v[104:105], v[104:105], v[104:105] op_sel:[0,1] op_sel_hi:[1,0]
	v_pk_add_f32 v[106:107], v[110:111], v[114:115]
	v_pk_add_f32 v[108:109], v[108:109], v[118:119]
	v_pk_add_f32 v[110:111], v[112:113], v[122:123]
	v_pk_mov_b32 v[112:113], v[126:127], v[124:125] op_sel:[1,0]
	v_mov_b32_e32 v127, v125
	v_pk_mov_b32 v[114:115], v[130:131], v[128:129] op_sel:[1,0]
	v_mov_b32_e32 v131, v129
	v_mul_f32_e32 v136, v48, v48
	v_mul_f32_e32 v137, v49, v49
	v_mul_f32_e32 v132, v37, v37
	v_mul_f32_e32 v134, v39, v39
	v_mov_b32_e32 v117, v138
	v_mov_b32_e32 v121, v139
	v_pk_add_f32 v[98:99], v[98:99], v[102:103]
	v_mov_b32_e32 v101, v133
	v_mov_b32_e32 v105, v135
	v_pk_add_f32 v[102:103], v[108:109], v[108:109] op_sel:[0,1] op_sel_hi:[1,0]
	v_pk_add_f32 v[108:109], v[110:111], v[110:111] op_sel:[0,1] op_sel_hi:[1,0]
	v_pk_add_f32 v[112:113], v[112:113], v[126:127]
	v_pk_add_f32 v[114:115], v[114:115], v[130:131]
	v_mul_f32_e32 v93, v32, v32
	v_mul_f32_e32 v140, v33, v33
	v_mul_f32_e32 v141, v34, v34
	v_mul_f32_e32 v142, v35, v35
	v_pk_fma_f32 v[118:119], v[36:37], v[36:37], v[132:133] op_sel_hi:[1,1,0]
	v_pk_fma_f32 v[122:123], v[38:39], v[38:39], v[134:135] op_sel_hi:[1,1,0]
	v_pk_add_f32 v[110:111], v[116:117], v[120:121]
	v_add_f32_e32 v116, v98, v99
	v_pk_add_f32 v[98:99], v[100:101], v[104:105]
	v_mov_b32_e32 v103, v136
	v_mov_b32_e32 v109, v137
	v_pk_add_f32 v[100:101], v[112:113], v[112:113] op_sel:[0,1] op_sel_hi:[1,0]
	v_pk_add_f32 v[104:105], v[114:115], v[114:115] op_sel:[0,1] op_sel_hi:[1,0]
	v_mov_b32_e32 v119, v141
	v_mov_b32_e32 v123, v142
	v_pk_add_f32 v[98:99], v[98:99], v[106:107]
	v_pk_add_f32 v[102:103], v[102:103], v[108:109]
	v_mov_b32_e32 v101, v93
	v_mov_b32_e32 v105, v140
	v_pk_add_f32 v[112:113], v[118:119], v[122:123]
	v_add_f32_e32 v93, v98, v99
	v_pk_add_f32 v[98:99], v[102:103], v[110:111]
	v_pk_add_f32 v[100:101], v[100:101], v[104:105]
	v_add_f32_e32 v103, v98, v99
	v_pk_add_f32 v[98:99], v[100:101], v[112:113]
	v_add_f32_e32 v98, v98, v99
	s_waitcnt lgkmcnt(3)
	s_nop 1
	v_add_f32_dpp v101, v116, v116 quad_perm:[1,0,3,2] row_mask:0xf bank_mask:0xf
	s_waitcnt lgkmcnt(3)
	s_nop 1
	v_add_f32_dpp v93, v93, v93 quad_perm:[1,0,3,2] row_mask:0xf bank_mask:0xf
	s_waitcnt lgkmcnt(3)
	s_nop 1
	v_add_f32_dpp v100, v103, v103 quad_perm:[1,0,3,2] row_mask:0xf bank_mask:0xf
	s_waitcnt lgkmcnt(3)
	s_nop 1
	v_add_f32_dpp v98, v98, v98 quad_perm:[1,0,3,2] row_mask:0xf bank_mask:0xf
	s_waitcnt lgkmcnt(3)
	s_nop 1
	v_add_f32_dpp v101, v101, v101 quad_perm:[2,3,0,1] row_mask:0xf bank_mask:0xf
	s_waitcnt lgkmcnt(3)
	s_nop 1
	v_add_f32_dpp v93, v93, v93 quad_perm:[2,3,0,1] row_mask:0xf bank_mask:0xf
	s_waitcnt lgkmcnt(3)
	s_nop 1
	v_add_f32_dpp v100, v100, v100 quad_perm:[2,3,0,1] row_mask:0xf bank_mask:0xf
	s_waitcnt lgkmcnt(3)
	s_nop 1
	v_add_f32_dpp v98, v98, v98 quad_perm:[2,3,0,1] row_mask:0xf bank_mask:0xf
	s_waitcnt lgkmcnt(3)
	s_nop 1
	v_add_f32_dpp v101, v101, v101 row_half_mirror row_mask:0xf bank_mask:0xf
	s_waitcnt lgkmcnt(3)
	s_nop 1
	v_add_f32_dpp v93, v93, v93 row_half_mirror row_mask:0xf bank_mask:0xf
	s_waitcnt lgkmcnt(3)
	s_nop 1
	v_add_f32_dpp v100, v100, v100 row_half_mirror row_mask:0xf bank_mask:0xf
	s_waitcnt lgkmcnt(3)
	s_nop 1
	v_add_f32_dpp v98, v98, v98 row_half_mirror row_mask:0xf bank_mask:0xf
	s_waitcnt lgkmcnt(3)
	s_nop 1
	v_add_f32_dpp v101, v101, v101 row_mirror row_mask:0xf bank_mask:0xf
	v_mov_b32_e32 v104, v101
	s_waitcnt lgkmcnt(3)
	s_nop 1
	v_add_f32_dpp v93, v93, v93 row_mirror row_mask:0xf bank_mask:0xf
	v_mov_b32_e32 v102, v93
	s_waitcnt lgkmcnt(3)
	s_nop 1
	v_add_f32_dpp v100, v100, v100 row_mirror row_mask:0xf bank_mask:0xf
	v_mov_b32_e32 v103, v100
	s_waitcnt lgkmcnt(3)
	s_nop 1
	v_add_f32_dpp v98, v98, v98 row_mirror row_mask:0xf bank_mask:0xf
	v_mov_b32_e32 v99, v98
	s_waitcnt lgkmcnt(3)
	s_nop 1
	v_permlane16_swap_b32_e32 v104, v101
	v_add_f32_e32 v101, v101, v104
	v_mov_b32_e32 v104, v101
	s_waitcnt lgkmcnt(3)
	s_nop 1
	v_permlane16_swap_b32_e32 v102, v93
	v_add_f32_e32 v93, v93, v102
	v_mov_b32_e32 v102, v93
	s_waitcnt lgkmcnt(3)
	s_nop 1
	v_permlane16_swap_b32_e32 v103, v100
	v_add_f32_e32 v100, v100, v103
	v_mov_b32_e32 v103, v100
	s_waitcnt lgkmcnt(3)
	s_nop 1
	v_permlane16_swap_b32_e32 v99, v98
	v_add_f32_e32 v98, v98, v99
	v_mov_b32_e32 v99, v98
	s_waitcnt lgkmcnt(3)
	s_nop 1
	v_permlane32_swap_b32_e32 v104, v101
	v_add_f32_e32 v101, v101, v104
	v_fmamk_f32 v101, v101, 0x3a800000, v92
	v_mul_f32_e32 v104, 0x4b800000, v101
	s_waitcnt lgkmcnt(2)
	s_nop 1
	v_permlane32_swap_b32_e32 v102, v93
	v_add_f32_e32 v93, v93, v102
	v_cmp_gt_f32_e64 s[0:1], s14, v101
	v_fmamk_f32 v93, v93, 0x3a800000, v92
	s_waitcnt lgkmcnt(1)
	s_nop 1
	v_permlane32_swap_b32_e32 v103, v100
	v_add_f32_e32 v100, v100, v103
	v_cndmask_b32_e64 v101, v101, v104, s[0:1]
	v_rsq_f32_e32 v101, v101
	v_mul_f32_e32 v102, 0x4b800000, v93
	v_fmamk_f32 v100, v100, 0x3a800000, v92
	s_waitcnt lgkmcnt(0)
	s_nop 1
	v_permlane32_swap_b32_e32 v99, v98
	v_add_f32_e32 v98, v98, v99
	v_cmp_gt_f32_e64 s[2:3], s14, v93
	v_mul_f32_e32 v99, 0x4b800000, v100
	v_cmp_gt_f32_e64 s[4:5], s14, v100
	v_cndmask_b32_e64 v93, v93, v102, s[2:3]
	v_fmamk_f32 v98, v98, 0x3a800000, v92
	v_rsq_f32_e32 v93, v93
	v_cndmask_b32_e64 v99, v100, v99, s[4:5]
	v_mul_f32_e32 v100, 0x4b800000, v98
	v_cmp_gt_f32_e32 vcc, s14, v98
	v_rsq_f32_e32 v99, v99
	s_nop 0
	v_cndmask_b32_e32 v98, v98, v100, vcc
	v_mul_f32_e32 v100, 0x45800000, v101
	v_rsq_f32_e32 v98, v98
	v_cndmask_b32_e64 v100, v101, v100, s[0:1]
	v_mul_f32_e32 v28, v28, v100
	v_mul_f32_e32 v29, v29, v100
	v_mul_f32_e32 v30, v30, v100
	v_mul_f32_e32 v31, v31, v100
	v_mul_f32_e32 v24, v24, v100
	v_mul_f32_e32 v25, v25, v100
	v_mul_f32_e32 v26, v26, v100
	v_mul_f32_e32 v27, v27, v100
	v_mul_f32_e32 v20, v20, v100
	v_mul_f32_e32 v21, v21, v100
	v_mul_f32_e32 v22, v22, v100
	v_mul_f32_e32 v23, v23, v100
	v_mul_f32_e32 v16, v16, v100
	v_mul_f32_e32 v17, v17, v100
	v_mul_f32_e32 v18, v18, v100
	v_mul_f32_e32 v19, v19, v100
	v_mul_f32_e32 v100, 0x45800000, v93
	v_mul_f32_e32 v28, v12, v28
	v_mul_f32_e32 v29, v13, v29
	v_mul_f32_e32 v24, v8, v24
	v_mul_f32_e32 v25, v9, v25
	v_mul_f32_e32 v26, v10, v26
	v_mul_f32_e32 v20, v4, v20
	v_cndmask_b32_e64 v93, v93, v100, s[2:3]
	v_mul_f32_e32 v100, 0x45800000, v99
	v_mul_f32_e32 v30, v14, v30
	v_mul_f32_e32 v31, v15, v31
	v_mul_f32_e32 v27, v11, v27
	v_mul_f32_e32 v21, v5, v21
	v_mul_f32_e32 v22, v6, v22
	v_mul_f32_e32 v23, v7, v23
	v_mul_f32_e32 v101, v0, v16
	v_mul_f32_e32 v102, v1, v17
	v_mul_f32_e32 v103, v2, v18
	v_mul_f32_e32 v104, v3, v19
	v_cvt_pk_bf16_f32 v16, v28, v29
	v_cvt_pk_bf16_f32 v17, v30, v31
	v_cvt_pk_bf16_f32 v18, v24, v25
	v_cvt_pk_bf16_f32 v19, v26, v27
	v_cvt_pk_bf16_f32 v20, v20, v21
	v_mul_f32_e32 v24, v94, v93
	v_mul_f32_e32 v25, v95, v93
	v_mul_f32_e32 v26, v96, v93
	v_mul_f32_e32 v28, v72, v93
	v_mul_f32_e32 v29, v73, v93
	v_mul_f32_e32 v68, v68, v93
	v_mul_f32_e32 v69, v69, v93
	v_mul_f32_e32 v64, v64, v93
	v_cndmask_b32_e64 v72, v99, v100, s[4:5]
	v_mul_f32_e32 v73, 0x45800000, v98
	v_cvt_pk_bf16_f32 v21, v22, v23
	v_cvt_pk_bf16_f32 v22, v101, v102
	v_cvt_pk_bf16_f32 v23, v103, v104
	v_mul_f32_e32 v27, v97, v93
	v_mul_f32_e32 v30, v74, v93
	v_mul_f32_e32 v31, v75, v93
	v_mul_f32_e32 v70, v70, v93
	v_mul_f32_e32 v71, v71, v93
	global_store_dwordx2 v[80:81], v[16:17], off
	global_store_dwordx2 v[80:81], v[18:19], off offset:512
	global_store_dwordx2 v[80:81], v[20:21], off offset:1024
	global_store_dwordx2 v[80:81], v[22:23], off offset:1536
	v_mul_f32_e32 v16, v12, v24
	v_mul_f32_e32 v17, v13, v25
	v_mul_f32_e32 v18, v14, v26
	v_mul_f32_e32 v20, v8, v28
	v_mul_f32_e32 v24, v4, v68
	v_mul_f32_e32 v25, v5, v69
	v_mul_f32_e32 v28, v0, v64
	v_mul_f32_e32 v60, v60, v72
	v_mul_f32_e32 v61, v61, v72
	v_cndmask_b32_e32 v64, v98, v73, vcc
	v_mul_f32_e32 v65, v65, v93
	v_mul_f32_e32 v66, v66, v93
	v_mul_f32_e32 v67, v67, v93
	v_mul_f32_e32 v19, v15, v27
	v_mul_f32_e32 v21, v9, v29
	v_mul_f32_e32 v22, v10, v30
	v_mul_f32_e32 v23, v11, v31
	v_mul_f32_e32 v26, v6, v70
	v_mul_f32_e32 v27, v7, v71
	v_mul_f32_e32 v62, v62, v72
	v_mul_f32_e32 v63, v63, v72
	v_mul_f32_e32 v52, v52, v72
	v_mul_f32_e32 v53, v53, v72
	v_mul_f32_e32 v54, v54, v72
	v_mul_f32_e32 v55, v55, v72
	v_mul_f32_e32 v48, v48, v72
	v_mul_f32_e32 v49, v49, v72
	v_cvt_pk_bf16_f32 v16, v16, v17
	v_cvt_pk_bf16_f32 v17, v18, v19
	v_cvt_pk_bf16_f32 v18, v20, v21
	v_cvt_pk_bf16_f32 v20, v24, v25
	v_mul_f32_e32 v24, v12, v60
	v_mul_f32_e32 v25, v13, v61
	v_mul_f32_e32 v44, v44, v64
	v_mul_f32_e32 v45, v45, v64
	v_mul_f32_e32 v46, v46, v64
	v_mul_f32_e32 v47, v47, v64
	v_mul_f32_e32 v36, v36, v64
	v_mul_f32_e32 v37, v37, v64
	v_mul_f32_e32 v38, v38, v64
	v_mul_f32_e32 v39, v39, v64
	v_mul_f32_e32 v32, v32, v64
	v_mul_f32_e32 v33, v33, v64
	v_mul_f32_e32 v29, v1, v65
	v_mul_f32_e32 v30, v2, v66
	v_mul_f32_e32 v31, v3, v67
	v_mul_f32_e32 v56, v56, v72
	v_mul_f32_e32 v57, v57, v72
	v_mul_f32_e32 v58, v58, v72
	v_mul_f32_e32 v59, v59, v72
	v_mul_f32_e32 v50, v50, v72
	v_mul_f32_e32 v51, v51, v72
	v_cvt_pk_bf16_f32 v19, v22, v23
	v_cvt_pk_bf16_f32 v21, v26, v27
	v_cvt_pk_bf16_f32 v22, v28, v29
	v_cvt_pk_bf16_f32 v23, v30, v31
	v_mul_f32_e32 v26, v14, v62
	v_mul_f32_e32 v27, v15, v63
	v_mul_f32_e32 v52, v4, v52
	v_mul_f32_e32 v53, v5, v53
	v_mul_f32_e32 v54, v6, v54
	v_mul_f32_e32 v55, v7, v55
	v_mul_f32_e32 v48, v0, v48
	v_mul_f32_e32 v49, v1, v49
	v_mul_f32_e32 v40, v40, v64
	v_mul_f32_e32 v41, v41, v64
	v_mul_f32_e32 v42, v42, v64
	v_mul_f32_e32 v43, v43, v64
	v_mul_f32_e32 v34, v34, v64
	v_mul_f32_e32 v35, v35, v64
	global_store_dwordx2 v[80:81], v[16:17], off offset:2048
	global_store_dwordx2 v[80:81], v[18:19], off offset:2560
	global_store_dwordx2 v[80:81], v[20:21], off offset:3072
	global_store_dwordx2 v[80:81], v[22:23], off offset:3584
	v_cvt_pk_bf16_f32 v16, v24, v25
	v_cvt_pk_bf16_f32 v17, v26, v27
	v_mul_f32_e32 v12, v12, v44
	v_mul_f32_e32 v13, v13, v45
	v_mul_f32_e32 v14, v14, v46
	v_mul_f32_e32 v15, v15, v47
	v_mul_f32_e32 v4, v4, v36
	v_mul_f32_e32 v5, v5, v37
	v_mul_f32_e32 v6, v6, v38
	v_mul_f32_e32 v7, v7, v39
	v_mul_f32_e32 v24, v0, v32
	v_mul_f32_e32 v25, v1, v33
	v_lshl_add_u64 v[80:81], v[80:81], 0, s[10:11]
	v_cvt_pk_bf16_f32 v0, v12, v13
	v_cvt_pk_bf16_f32 v1, v14, v15
	v_mul_f32_e32 v28, v8, v56
	v_mul_f32_e32 v29, v9, v57
	v_mul_f32_e32 v30, v10, v58
	v_mul_f32_e32 v31, v11, v59
	v_mul_f32_e32 v50, v2, v50
	v_mul_f32_e32 v51, v3, v51
	v_cvt_pk_bf16_f32 v18, v28, v29
	v_cvt_pk_bf16_f32 v19, v30, v31
	v_cvt_pk_bf16_f32 v20, v52, v53
	v_cvt_pk_bf16_f32 v21, v54, v55
	v_cvt_pk_bf16_f32 v22, v48, v49
	v_cvt_pk_bf16_f32 v23, v50, v51
	v_mul_f32_e32 v8, v8, v40
	v_mul_f32_e32 v9, v9, v41
	v_mul_f32_e32 v10, v10, v42
	v_mul_f32_e32 v11, v11, v43
	v_mul_f32_e32 v26, v2, v34
	v_mul_f32_e32 v27, v3, v35
	global_store_dwordx2 v[84:85], v[16:17], off
	global_store_dwordx2 v[84:85], v[18:19], off offset:512
	global_store_dwordx2 v[84:85], v[20:21], off offset:1024
	global_store_dwordx2 v[84:85], v[22:23], off offset:1536
	v_cvt_pk_bf16_f32 v2, v8, v9
	v_cvt_pk_bf16_f32 v3, v10, v11
	v_cvt_pk_bf16_f32 v4, v4, v5
	v_cvt_pk_bf16_f32 v5, v6, v7
	v_cvt_pk_bf16_f32 v6, v24, v25
	v_cvt_pk_bf16_f32 v7, v26, v27
	global_store_dwordx2 v[84:85], v[0:1], off offset:2048
	global_store_dwordx2 v[84:85], v[2:3], off offset:2560
	global_store_dwordx2 v[84:85], v[4:5], off offset:3072
	global_store_dwordx2 v[84:85], v[6:7], off offset:3584
	s_cbranch_scc0 .LBB0_1710

.LBB0_1713:
	global_load_dwordx4 v[164:167], v[4:5], off
	global_load_dwordx4 v[168:171], v[4:5], off offset:1024
	global_load_dwordx4 v[172:175], v[4:5], off offset:2048
	global_load_dwordx4 v[176:179], v[4:5], off offset:3072
	v_lshl_add_u64 v[6:7], s[8:9], 0, v[2:3]
	v_add_co_u32_e64 v30, s[0:1], s10, v6
	v_lshl_add_u64 v[8:9], s[2:3], 0, v[2:3]
	s_nop 0
	v_addc_co_u32_e64 v31, s[0:1], 0, v7, s[0:1]
	v_add_co_u32_e32 v158, vcc, 0x4000000, v8
	v_add_co_u32_e64 v46, s[0:1], s11, v6
	s_nop 0
	v_addc_co_u32_e32 v159, vcc, 0, v9, vcc
	v_addc_co_u32_e64 v47, s[0:1], 0, v7, s[0:1]
	v_add_co_u32_e64 v62, s[0:1], s12, v6
	v_add_co_u32_e32 v8, vcc, 0x14114000, v6
	s_nop 0
	v_addc_co_u32_e64 v63, s[0:1], 0, v7, s[0:1]
	v_addc_co_u32_e32 v9, vcc, 0, v7, vcc
	v_add_co_u32_e64 v78, s[0:1], s13, v6
	v_add_co_u32_e32 v126, vcc, 0x14314000, v6
	s_nop 0
	v_addc_co_u32_e64 v79, s[0:1], 0, v7, s[0:1]
	v_addc_co_u32_e32 v127, vcc, 0, v7, vcc
	global_load_dwordx4 v[18:21], v[30:31], off
	global_load_dwordx4 v[22:25], v[30:31], off offset:1024
	global_load_dwordx4 v[26:29], v[30:31], off offset:2048
	s_nop 0
	global_load_dwordx4 v[30:33], v[30:31], off offset:3072
	s_nop 0
	global_load_dwordx4 v[34:37], v[46:47], off
	global_load_dwordx4 v[38:41], v[46:47], off offset:1024
	global_load_dwordx4 v[42:45], v[46:47], off offset:2048
	s_nop 0
	global_load_dwordx4 v[46:49], v[46:47], off offset:3072
	s_nop 0
	global_load_dwordx4 v[50:53], v[62:63], off
	global_load_dwordx4 v[54:57], v[62:63], off offset:1024
	global_load_dwordx4 v[58:61], v[62:63], off offset:2048
	s_nop 0
	global_load_dwordx4 v[62:65], v[62:63], off offset:3072
	s_nop 0
	global_load_dwordx4 v[66:69], v[78:79], off
	global_load_dwordx4 v[70:73], v[78:79], off offset:1024
	global_load_dwordx4 v[74:77], v[78:79], off offset:2048
	s_nop 0
	global_load_dwordx4 v[78:81], v[78:79], off offset:3072
	s_nop 0
	global_load_dwordx4 v[82:85], v[158:159], off
	global_load_dwordx4 v[86:89], v[158:159], off offset:1024
	global_load_dwordx4 v[90:93], v[158:159], off offset:2048
	global_load_dwordx4 v[94:97], v[158:159], off offset:3072
	global_load_dwordx4 v[98:101], v[8:9], off
	global_load_dwordx4 v[102:105], v[8:9], off offset:1024
	global_load_dwordx4 v[106:109], v[8:9], off offset:2048
	global_load_dwordx4 v[110:113], v[8:9], off offset:3072
	v_add_co_u32_e32 v8, vcc, 0x14514000, v6
	global_load_dwordx4 v[114:117], v[126:127], off
	global_load_dwordx4 v[118:121], v[126:127], off offset:1024
	global_load_dwordx4 v[122:125], v[126:127], off offset:2048
	s_nop 0
	global_load_dwordx4 v[126:129], v[126:127], off offset:3072
	v_addc_co_u32_e32 v9, vcc, 0, v7, vcc
	v_add_co_u32_e32 v154, vcc, 0x14714000, v6
	global_load_dwordx4 v[130:133], v[8:9], off
	global_load_dwordx4 v[134:137], v[8:9], off offset:1024
	global_load_dwordx4 v[138:141], v[8:9], off offset:2048
	global_load_dwordx4 v[142:145], v[8:9], off offset:3072
	v_addc_co_u32_e32 v155, vcc, 0, v7, vcc
	global_load_dwordx4 v[6:9], v[154:155], off
	global_load_dwordx4 v[146:149], v[154:155], off offset:1024
	global_load_dwordx4 v[150:153], v[154:155], off offset:2048
	s_nop 0
	global_load_dwordx4 v[154:157], v[154:155], off offset:3072
	s_add_i32 s16, s15, 0x4000
	s_ashr_i32 s17, s16, 31
	s_lshl_b64 s[0:1], s[16:17], 11
	v_lshl_add_u64 v[160:161], v[0:1], 0, s[0:1]
	s_add_i32 s15, s15, s92
	s_add_u32 s2, s2, s4
	s_addc_u32 s3, s3, s5
	s_add_u32 s8, s8, s4
	s_addc_u32 s9, s9, s5
	s_cmpk_lt_i32 s15, 0x200
	s_waitcnt vmcnt(0)
	v_pk_add_f32 v[84:85], v[84:85], v[100:101]
	v_pk_add_f32 v[82:83], v[82:83], v[98:99]
	v_pk_add_f32 v[88:89], v[88:89], v[104:105]
	v_pk_add_f32 v[86:87], v[86:87], v[102:103]
	v_pk_add_f32 v[92:93], v[92:93], v[108:109]
	v_pk_add_f32 v[90:91], v[90:91], v[106:107]
	v_pk_add_f32 v[96:97], v[96:97], v[112:113]
	v_pk_add_f32 v[94:95], v[94:95], v[110:111]
	v_pk_add_f32 v[84:85], v[84:85], v[116:117]
	v_pk_add_f32 v[82:83], v[82:83], v[114:115]
	v_pk_add_f32 v[88:89], v[88:89], v[120:121]
	v_pk_add_f32 v[86:87], v[86:87], v[118:119]
	v_pk_add_f32 v[92:93], v[92:93], v[124:125]
	v_pk_add_f32 v[90:91], v[90:91], v[122:123]
	v_pk_add_f32 v[96:97], v[96:97], v[128:129]
	v_pk_add_f32 v[94:95], v[94:95], v[126:127]
	v_pk_add_f32 v[84:85], v[84:85], v[132:133]
	v_pk_add_f32 v[82:83], v[82:83], v[130:131]
	v_pk_add_f32 v[88:89], v[88:89], v[136:137]
	v_pk_add_f32 v[86:87], v[86:87], v[134:135]
	v_pk_add_f32 v[92:93], v[92:93], v[140:141]
	v_pk_add_f32 v[90:91], v[90:91], v[138:139]
	v_pk_add_f32 v[96:97], v[96:97], v[144:145]
	v_pk_add_f32 v[94:95], v[94:95], v[142:143]
	v_pk_add_f32 v[8:9], v[84:85], v[8:9]
	v_pk_add_f32 v[6:7], v[82:83], v[6:7]
	v_pk_add_f32 v[82:83], v[88:89], v[148:149]
	v_pk_add_f32 v[84:85], v[86:87], v[146:147]
	v_pk_add_f32 v[86:87], v[92:93], v[152:153]
	v_pk_add_f32 v[88:89], v[90:91], v[150:151]
	v_pk_add_f32 v[90:91], v[96:97], v[156:157]
	v_pk_add_f32 v[92:93], v[94:95], v[154:155]
	v_pk_add_f32 v[8:9], v[8:9], v[20:21]
	v_pk_add_f32 v[6:7], v[6:7], v[18:19]
	v_pk_add_f32 v[18:19], v[82:83], v[24:25]
	v_pk_add_f32 v[20:21], v[84:85], v[22:23]
	v_pk_add_f32 v[22:23], v[86:87], v[28:29]
	v_pk_add_f32 v[24:25], v[88:89], v[26:27]
	v_pk_add_f32 v[26:27], v[90:91], v[32:33]
	v_pk_add_f32 v[28:29], v[92:93], v[30:31]
	v_pk_add_f32 v[8:9], v[8:9], v[36:37]
	v_pk_add_f32 v[6:7], v[6:7], v[34:35]
	v_pk_add_f32 v[18:19], v[18:19], v[40:41]
	v_pk_add_f32 v[20:21], v[20:21], v[38:39]
	v_pk_add_f32 v[22:23], v[22:23], v[44:45]
	v_pk_add_f32 v[24:25], v[24:25], v[42:43]
	v_pk_add_f32 v[26:27], v[26:27], v[48:49]
	v_pk_add_f32 v[28:29], v[28:29], v[46:47]
	v_pk_add_f32 v[8:9], v[8:9], v[52:53]
	v_pk_add_f32 v[6:7], v[6:7], v[50:51]
	v_pk_add_f32 v[18:19], v[18:19], v[56:57]
	v_pk_add_f32 v[30:31], v[20:21], v[54:55]
	v_pk_add_f32 v[22:23], v[22:23], v[60:61]
	v_pk_add_f32 v[32:33], v[24:25], v[58:59]
	v_pk_add_f32 v[26:27], v[26:27], v[64:65]
	v_pk_add_f32 v[34:35], v[28:29], v[62:63]
	v_pk_add_f32 v[8:9], v[8:9], v[68:69]
	v_pk_add_f32 v[6:7], v[6:7], v[66:67]
	v_pk_add_f32 v[20:21], v[18:19], v[72:73]
	v_pk_add_f32 v[18:19], v[30:31], v[70:71]
	v_pk_add_f32 v[24:25], v[22:23], v[76:77]
	v_pk_add_f32 v[22:23], v[32:33], v[74:75]
	v_pk_add_f32 v[28:29], v[26:27], v[80:81]
	v_pk_add_f32 v[26:27], v[34:35], v[78:79]
	global_store_dwordx4 v[158:159], v[6:9], off
	global_store_dwordx4 v[158:159], v[18:21], off offset:1024
	global_store_dwordx4 v[158:159], v[22:25], off offset:2048
	global_store_dwordx4 v[158:159], v[26:29], off offset:3072
	v_pk_mul_f32 v[34:35], v[8:9], v[8:9]
	v_pk_mul_f32 v[36:37], v[6:7], v[6:7]
	v_pk_mul_f32 v[38:39], v[20:21], v[20:21]
	v_pk_mul_f32 v[40:41], v[18:19], v[18:19]
	v_pk_mov_b32 v[46:47], v[36:37], v[34:35] op_sel:[1,0]
	v_mov_b32_e32 v37, v35
	v_pk_mov_b32 v[34:35], v[40:41], v[38:39] op_sel:[1,0]
	v_mov_b32_e32 v41, v39
	v_mul_f32_e32 v45, v27, v27
	v_mul_f32_e32 v42, v23, v23
	v_mul_f32_e32 v44, v25, v25
	v_pk_add_f32 v[36:37], v[46:47], v[36:37]
	v_pk_add_f32 v[34:35], v[34:35], v[40:41]
	v_mul_f32_e32 v17, v26, v26
	v_mul_f32_e32 v48, v28, v28
	v_mul_f32_e32 v49, v29, v29
	v_pk_fma_f32 v[38:39], v[22:23], v[22:23], v[42:43] op_sel_hi:[1,1,0]
	v_pk_fma_f32 v[42:43], v[24:25], v[24:25], v[44:45] op_sel_hi:[1,1,0]
	v_pk_add_f32 v[36:37], v[36:37], v[36:37] op_sel:[0,1] op_sel_hi:[1,0]
	v_pk_add_f32 v[34:35], v[34:35], v[34:35] op_sel:[0,1] op_sel_hi:[1,0]
	v_mov_b32_e32 v39, v48
	v_mov_b32_e32 v43, v49
	v_mov_b32_e32 v37, v17
	v_mov_b32_e32 v35, v45
	v_pk_add_f32 v[38:39], v[38:39], v[42:43]
	v_pk_add_f32 v[34:35], v[36:37], v[34:35]
	s_nop 0
	v_pk_add_f32 v[34:35], v[34:35], v[38:39]
	s_nop 0
	v_add_f32_e32 v17, v34, v35
	s_waitcnt lgkmcnt(0)
	s_nop 1
	v_add_f32_dpp v17, v17, v17 quad_perm:[1,0,3,2] row_mask:0xf bank_mask:0xf
	s_waitcnt lgkmcnt(0)
	s_nop 1
	v_add_f32_dpp v17, v17, v17 quad_perm:[2,3,0,1] row_mask:0xf bank_mask:0xf
	s_waitcnt lgkmcnt(0)
	s_nop 1
	v_add_f32_dpp v17, v17, v17 row_half_mirror row_mask:0xf bank_mask:0xf
	s_waitcnt lgkmcnt(0)
	s_nop 1
	v_add_f32_dpp v17, v17, v17 row_mirror row_mask:0xf bank_mask:0xf
	v_mov_b32_e32 v34, v17
	s_waitcnt lgkmcnt(0)
	s_nop 1
	v_permlane16_swap_b32_e32 v34, v17
	v_add_f32_e32 v17, v17, v34
	v_mov_b32_e32 v34, v17
	s_waitcnt lgkmcnt(0)
	s_nop 1
	v_permlane32_swap_b32_e32 v34, v17
	v_add_f32_e32 v17, v17, v34
	v_fmamk_f32 v17, v17, 0x3a800000, v16
	v_mul_f32_e32 v34, 0x4b800000, v17
	v_cmp_gt_f32_e32 vcc, s14, v17
	s_nop 1
	v_cndmask_b32_e32 v17, v17, v34, vcc
	v_rsq_f32_e32 v17, v17
	s_nop 0
	v_mul_f32_e32 v34, 0x45800000, v17
	v_cndmask_b32_e32 v17, v17, v34, vcc
	v_mul_f32_e32 v6, v6, v17
	v_mul_f32_e32 v7, v7, v17
	v_mul_f32_e32 v8, v8, v17
	v_mul_f32_e32 v9, v9, v17
	v_mul_f32_e32 v6, v164, v6
	v_mul_f32_e32 v7, v165, v7
	v_mul_f32_e32 v8, v166, v8
	v_mul_f32_e32 v9, v167, v9
	v_cvt_pk_bf16_f32 v6, v6, v7
	v_cvt_pk_bf16_f32 v7, v8, v9
	global_store_dwordx2 v[160:161], v[6:7], off
	v_mul_f32_e32 v18, v18, v17
	v_mul_f32_e32 v19, v19, v17
	v_mul_f32_e32 v20, v20, v17
	v_mul_f32_e32 v21, v21, v17
	v_mul_f32_e32 v6, v168, v18
	v_mul_f32_e32 v7, v169, v19
	v_mul_f32_e32 v8, v170, v20
	v_mul_f32_e32 v9, v171, v21
	v_cvt_pk_bf16_f32 v6, v6, v7
	v_cvt_pk_bf16_f32 v7, v8, v9
	global_store_dwordx2 v[160:161], v[6:7], off offset:512
	v_mul_f32_e32 v18, v22, v17
	v_mul_f32_e32 v19, v23, v17
	v_mul_f32_e32 v20, v24, v17
	v_mul_f32_e32 v21, v25, v17
	v_mul_f32_e32 v6, v18, v172
	v_mul_f32_e32 v7, v19, v173
	v_mul_f32_e32 v8, v20, v174
	v_mul_f32_e32 v9, v21, v175
	v_cvt_pk_bf16_f32 v6, v6, v7
	v_cvt_pk_bf16_f32 v7, v8, v9
	global_store_dwordx2 v[160:161], v[6:7], off offset:1024
	v_mul_f32_e32 v18, v26, v17
	v_mul_f32_e32 v19, v27, v17
	v_mul_f32_e32 v20, v28, v17
	v_mul_f32_e32 v17, v29, v17
	v_mul_f32_e32 v6, v18, v176
	v_mul_f32_e32 v7, v19, v177
	v_mul_f32_e32 v8, v20, v178
	v_mul_f32_e32 v9, v17, v179
	v_cvt_pk_bf16_f32 v6, v6, v7
	v_cvt_pk_bf16_f32 v7, v8, v9
	global_store_dwordx2 v[160:161], v[6:7], off offset:1536
	s_cbranch_scc1 .LBB0_1713

.LBB0_1955:
	s_nop 0
	v_lshl_add_u64 v[6:7], s[6:7], 0, v[0:1]
	v_add_co_u32_e64 v82, s[0:1], s8, v6
	v_lshl_add_u64 v[8:9], s[2:3], 0, v[0:1]
	s_nop 0
	v_addc_co_u32_e64 v83, s[0:1], 0, v7, s[0:1]
	v_add_co_u32_e64 v84, s[0:1], s9, v6
	v_add_co_u32_e32 v8, vcc, 0x4000000, v8
	s_nop 0
	v_addc_co_u32_e64 v85, s[0:1], 0, v7, s[0:1]
	v_add_co_u32_e64 v86, s[0:1], s10, v6
	v_addc_co_u32_e32 v9, vcc, 0, v9, vcc
	s_nop 0
	v_addc_co_u32_e64 v87, s[0:1], 0, v7, s[0:1]
	v_add_co_u32_e64 v118, s[0:1], s11, v6
	v_add_co_u32_e32 v162, vcc, 0x14114000, v6
	s_nop 0
	v_addc_co_u32_e64 v119, s[0:1], 0, v7, s[0:1]
	v_add_co_u32_e64 v120, s[0:1], s12, v6
	v_addc_co_u32_e32 v163, vcc, 0, v7, vcc
	s_nop 0
	v_addc_co_u32_e64 v121, s[0:1], 0, v7, s[0:1]
	v_add_co_u32_e64 v122, s[0:1], s13, v6
	global_load_dwordx4 v[18:21], v[2:3], off
	global_load_dwordx4 v[212:215], v[2:3], off offset:1024
	global_load_dwordx4 v[216:219], v[2:3], off offset:2048
	global_load_dwordx4 v[220:223], v[2:3], off offset:3072
	s_nop 0
	v_addc_co_u32_e64 v123, s[0:1], 0, v7, s[0:1]
	v_add_co_u32_e64 v130, s[0:1], s14, v6
	s_add_i32 s16, s18, 0x4000
	s_nop 0
	v_addc_co_u32_e64 v131, s[0:1], 0, v7, s[0:1]
	global_load_dwordx4 v[22:25], v[82:83], off
	global_load_dwordx4 v[26:29], v[82:83], off offset:1024
	global_load_dwordx4 v[30:33], v[82:83], off offset:2048
	global_load_dwordx4 v[34:37], v[82:83], off offset:3072
	global_load_dwordx4 v[38:41], v[84:85], off
	global_load_dwordx4 v[42:45], v[84:85], off offset:1024
	global_load_dwordx4 v[46:49], v[84:85], off offset:2048
	global_load_dwordx4 v[50:53], v[84:85], off offset:3072
	global_load_dwordx4 v[54:57], v[86:87], off
	global_load_dwordx4 v[58:61], v[86:87], off offset:1024
	global_load_dwordx4 v[62:65], v[86:87], off offset:2048
	global_load_dwordx4 v[66:69], v[86:87], off offset:3072
	global_load_dwordx4 v[70:73], v[118:119], off
	global_load_dwordx4 v[74:77], v[118:119], off offset:1024
	global_load_dwordx4 v[78:81], v[118:119], off offset:2048
	global_load_dwordx4 v[82:85], v[118:119], off offset:3072
	s_nop 0
	global_load_dwordx4 v[86:89], v[120:121], off
	global_load_dwordx4 v[90:93], v[120:121], off offset:1024
	global_load_dwordx4 v[94:97], v[120:121], off offset:2048
	global_load_dwordx4 v[98:101], v[120:121], off offset:3072
	global_load_dwordx4 v[102:105], v[122:123], off
	global_load_dwordx4 v[106:109], v[122:123], off offset:1024
	global_load_dwordx4 v[110:113], v[122:123], off offset:2048
	global_load_dwordx4 v[114:117], v[122:123], off offset:3072
	s_nop 0
	global_load_dwordx4 v[118:121], v[130:131], off
	global_load_dwordx4 v[122:125], v[130:131], off offset:1024
	global_load_dwordx4 v[126:129], v[130:131], off offset:2048
	s_nop 0
	global_load_dwordx4 v[130:133], v[130:131], off offset:3072
	s_nop 0
	global_load_dwordx4 v[134:137], v[8:9], off
	global_load_dwordx4 v[138:141], v[8:9], off offset:1024
	global_load_dwordx4 v[142:145], v[8:9], off offset:2048
	global_load_dwordx4 v[146:149], v[8:9], off offset:3072
	v_add_co_u32_e32 v8, vcc, 0x14314000, v6
	global_load_dwordx4 v[150:153], v[162:163], off
	global_load_dwordx4 v[154:157], v[162:163], off offset:1024
	global_load_dwordx4 v[158:161], v[162:163], off offset:2048
	s_nop 0
	global_load_dwordx4 v[162:165], v[162:163], off offset:3072
	v_addc_co_u32_e32 v9, vcc, 0, v7, vcc
	v_add_co_u32_e32 v194, vcc, 0x14514000, v6
	global_load_dwordx4 v[166:169], v[8:9], off
	global_load_dwordx4 v[170:173], v[8:9], off offset:1024
	global_load_dwordx4 v[174:177], v[8:9], off offset:2048
	global_load_dwordx4 v[178:181], v[8:9], off offset:3072
	v_addc_co_u32_e32 v195, vcc, 0, v7, vcc
	v_add_co_u32_e32 v206, vcc, 0x14714000, v6
	global_load_dwordx4 v[182:185], v[194:195], off
	global_load_dwordx4 v[186:189], v[194:195], off offset:1024
	global_load_dwordx4 v[190:193], v[194:195], off offset:2048
	s_nop 0
	global_load_dwordx4 v[194:197], v[194:195], off offset:3072
	v_addc_co_u32_e32 v207, vcc, 0, v7, vcc
	global_load_dwordx4 v[6:9], v[206:207], off
	global_load_dwordx4 v[198:201], v[206:207], off offset:1024
	global_load_dwordx4 v[202:205], v[206:207], off offset:2048
	s_nop 0
	global_load_dwordx4 v[206:209], v[206:207], off offset:3072
	s_ashr_i32 s17, s16, 31
	s_lshl_b64 s[0:1], s[16:17], 12
	v_lshl_add_u64 v[210:211], v[4:5], 0, s[0:1]
	s_add_i32 s18, s18, s92
	s_add_u32 s2, s2, s4
	s_addc_u32 s3, s3, s5
	s_add_u32 s6, s6, s4
	s_addc_u32 s7, s7, s5
	s_cmpk_gt_i32 s18, 0x1ff
	s_waitcnt vmcnt(0)
	v_pk_add_f32 v[136:137], v[136:137], v[152:153]
	v_pk_add_f32 v[134:135], v[134:135], v[150:151]
	v_pk_add_f32 v[140:141], v[140:141], v[156:157]
	v_pk_add_f32 v[138:139], v[138:139], v[154:155]
	v_pk_add_f32 v[144:145], v[144:145], v[160:161]
	v_pk_add_f32 v[136:137], v[136:137], v[168:169]
	v_pk_add_f32 v[134:135], v[134:135], v[166:167]
	v_pk_add_f32 v[140:141], v[140:141], v[172:173]
	v_pk_add_f32 v[138:139], v[138:139], v[170:171]
	v_pk_add_f32 v[142:143], v[142:143], v[158:159]
	v_pk_add_f32 v[146:147], v[146:147], v[162:163]
	v_pk_add_f32 v[136:137], v[136:137], v[184:185]
	v_pk_add_f32 v[134:135], v[134:135], v[182:183]
	v_pk_add_f32 v[140:141], v[140:141], v[188:189]
	v_pk_add_f32 v[138:139], v[138:139], v[186:187]
	v_pk_add_f32 v[148:149], v[148:149], v[164:165]
	v_pk_add_f32 v[144:145], v[144:145], v[176:177]
	v_pk_add_f32 v[142:143], v[142:143], v[174:175]
	v_pk_add_f32 v[146:147], v[146:147], v[178:179]
	v_pk_add_f32 v[8:9], v[136:137], v[8:9]
	v_pk_add_f32 v[6:7], v[134:135], v[6:7]
	v_pk_add_f32 v[134:135], v[140:141], v[200:201]
	v_pk_add_f32 v[136:137], v[138:139], v[198:199]
	v_pk_add_f32 v[148:149], v[148:149], v[180:181]
	v_pk_add_f32 v[144:145], v[144:145], v[192:193]
	v_pk_add_f32 v[142:143], v[142:143], v[190:191]
	v_pk_add_f32 v[146:147], v[146:147], v[194:195]
	v_pk_add_f32 v[8:9], v[8:9], v[24:25]
	v_pk_add_f32 v[6:7], v[6:7], v[22:23]
	v_pk_add_f32 v[22:23], v[134:135], v[28:29]
	v_pk_add_f32 v[24:25], v[136:137], v[26:27]
	v_pk_add_f32 v[148:149], v[148:149], v[196:197]
	v_pk_add_f32 v[138:139], v[144:145], v[204:205]
	v_pk_add_f32 v[140:141], v[142:143], v[202:203]
	v_pk_add_f32 v[144:145], v[146:147], v[206:207]
	v_pk_add_f32 v[8:9], v[8:9], v[40:41]
	v_pk_add_f32 v[6:7], v[6:7], v[38:39]
	v_pk_add_f32 v[22:23], v[22:23], v[44:45]
	v_pk_add_f32 v[24:25], v[24:25], v[42:43]
	v_pk_add_f32 v[142:143], v[148:149], v[208:209]
	v_pk_add_f32 v[26:27], v[138:139], v[32:33]
	v_pk_add_f32 v[28:29], v[140:141], v[30:31]
	v_pk_add_f32 v[32:33], v[144:145], v[34:35]
	v_pk_add_f32 v[8:9], v[8:9], v[56:57]
	v_pk_add_f32 v[6:7], v[6:7], v[54:55]
	v_pk_add_f32 v[22:23], v[22:23], v[60:61]
	v_pk_add_f32 v[24:25], v[24:25], v[58:59]
	v_pk_add_f32 v[30:31], v[142:143], v[36:37]
	v_pk_add_f32 v[26:27], v[26:27], v[48:49]
	v_pk_add_f32 v[28:29], v[28:29], v[46:47]
	v_pk_add_f32 v[32:33], v[32:33], v[50:51]
	v_pk_add_f32 v[8:9], v[8:9], v[72:73]
	v_pk_add_f32 v[6:7], v[6:7], v[70:71]
	v_pk_add_f32 v[22:23], v[22:23], v[76:77]
	v_pk_add_f32 v[24:25], v[24:25], v[74:75]
	v_pk_add_f32 v[30:31], v[30:31], v[52:53]
	v_pk_add_f32 v[26:27], v[26:27], v[64:65]
	v_pk_add_f32 v[28:29], v[28:29], v[62:63]
	v_pk_add_f32 v[32:33], v[32:33], v[66:67]
	v_pk_add_f32 v[8:9], v[8:9], v[88:89]
	v_pk_add_f32 v[6:7], v[6:7], v[86:87]
	v_pk_add_f32 v[22:23], v[22:23], v[92:93]
	v_pk_add_f32 v[24:25], v[24:25], v[90:91]
	v_pk_add_f32 v[30:31], v[30:31], v[68:69]
	v_pk_add_f32 v[26:27], v[26:27], v[80:81]
	v_pk_add_f32 v[28:29], v[28:29], v[78:79]
	v_pk_add_f32 v[32:33], v[32:33], v[82:83]
	v_pk_add_f32 v[8:9], v[8:9], v[104:105]
	v_pk_add_f32 v[6:7], v[6:7], v[102:103]
	v_pk_add_f32 v[22:23], v[22:23], v[108:109]
	v_pk_add_f32 v[24:25], v[24:25], v[106:107]
	v_pk_add_f32 v[30:31], v[30:31], v[84:85]
	v_pk_add_f32 v[26:27], v[26:27], v[96:97]
	v_pk_add_f32 v[28:29], v[28:29], v[94:95]
	v_pk_add_f32 v[32:33], v[32:33], v[98:99]
	v_pk_add_f32 v[8:9], v[8:9], v[120:121]
	v_pk_add_f32 v[6:7], v[6:7], v[118:119]
	v_pk_add_f32 v[22:23], v[22:23], v[124:125]
	v_pk_add_f32 v[24:25], v[24:25], v[122:123]
	v_pk_add_f32 v[30:31], v[30:31], v[100:101]
	v_pk_add_f32 v[26:27], v[26:27], v[112:113]
	v_pk_add_f32 v[28:29], v[28:29], v[110:111]
	v_pk_add_f32 v[32:33], v[32:33], v[114:115]
	v_pk_fma_f32 v[8:9], v[120:121], 0, v[8:9] op_sel_hi:[1,0,1]
	v_pk_fma_f32 v[6:7], v[118:119], 0, v[6:7] op_sel_hi:[1,0,1]
	v_pk_fma_f32 v[22:23], v[124:125], 0, v[22:23] op_sel_hi:[1,0,1]
	v_pk_fma_f32 v[24:25], v[122:123], 0, v[24:25] op_sel_hi:[1,0,1]
	v_pk_add_f32 v[30:31], v[30:31], v[116:117]
	v_pk_add_f32 v[26:27], v[26:27], v[128:129]
	v_pk_add_f32 v[28:29], v[28:29], v[126:127]
	v_pk_add_f32 v[32:33], v[32:33], v[130:131]
	v_pk_mul_f32 v[34:35], v[8:9], v[8:9]
	v_pk_mul_f32 v[36:37], v[6:7], v[6:7]
	v_pk_mul_f32 v[38:39], v[22:23], v[22:23]
	v_pk_mul_f32 v[40:41], v[24:25], v[24:25]
	v_pk_add_f32 v[30:31], v[30:31], v[132:133]
	v_pk_fma_f32 v[26:27], v[128:129], 0, v[26:27] op_sel_hi:[1,0,1]
	v_pk_fma_f32 v[28:29], v[126:127], 0, v[28:29] op_sel_hi:[1,0,1]
	v_pk_fma_f32 v[32:33], v[130:131], 0, v[32:33] op_sel_hi:[1,0,1]
	v_pk_mov_b32 v[46:47], v[36:37], v[34:35] op_sel:[1,0]
	v_mov_b32_e32 v37, v35
	v_pk_mov_b32 v[34:35], v[40:41], v[38:39] op_sel:[1,0]
	v_mov_b32_e32 v41, v39
	v_pk_fma_f32 v[30:31], v[132:133], 0, v[30:31] op_sel_hi:[1,0,1]
	v_mul_f32_e32 v45, v33, v33
	v_mul_f32_e32 v42, v29, v29
	v_mul_f32_e32 v44, v27, v27
	v_pk_add_f32 v[36:37], v[46:47], v[36:37]
	v_pk_add_f32 v[34:35], v[34:35], v[40:41]
	v_mul_f32_e32 v17, v32, v32
	v_mul_f32_e32 v48, v30, v30
	v_mul_f32_e32 v49, v31, v31
	v_pk_fma_f32 v[38:39], v[28:29], v[28:29], v[42:43] op_sel_hi:[1,1,0]
	v_pk_fma_f32 v[42:43], v[26:27], v[26:27], v[44:45] op_sel_hi:[1,1,0]
	v_pk_add_f32 v[36:37], v[36:37], v[36:37] op_sel:[0,1] op_sel_hi:[1,0]
	v_pk_add_f32 v[34:35], v[34:35], v[34:35] op_sel:[0,1] op_sel_hi:[1,0]
	v_mov_b32_e32 v39, v48
	v_mov_b32_e32 v43, v49
	v_mov_b32_e32 v37, v17
	v_mov_b32_e32 v35, v45
	v_pk_add_f32 v[38:39], v[38:39], v[42:43]
	v_pk_add_f32 v[34:35], v[36:37], v[34:35]
	s_nop 0
	v_pk_add_f32 v[34:35], v[34:35], v[38:39]
	s_nop 0
	v_add_f32_e32 v17, v34, v35
	s_waitcnt lgkmcnt(0)
	s_nop 1
	v_add_f32_dpp v17, v17, v17 quad_perm:[1,0,3,2] row_mask:0xf bank_mask:0xf
	s_waitcnt lgkmcnt(0)
	s_nop 1
	v_add_f32_dpp v17, v17, v17 quad_perm:[2,3,0,1] row_mask:0xf bank_mask:0xf
	s_waitcnt lgkmcnt(0)
	s_nop 1
	v_add_f32_dpp v17, v17, v17 row_half_mirror row_mask:0xf bank_mask:0xf
	s_waitcnt lgkmcnt(0)
	s_nop 1
	v_add_f32_dpp v17, v17, v17 row_mirror row_mask:0xf bank_mask:0xf
	v_mov_b32_e32 v34, v17
	s_waitcnt lgkmcnt(0)
	s_nop 1
	v_permlane16_swap_b32_e32 v34, v17
	v_add_f32_e32 v17, v17, v34
	v_mov_b32_e32 v34, v17
	s_waitcnt lgkmcnt(0)
	s_nop 1
	v_permlane32_swap_b32_e32 v34, v17
	v_add_f32_e32 v17, v17, v34
	v_fmamk_f32 v17, v17, 0x3a800000, v16
	v_mul_f32_e32 v34, 0x4b800000, v17
	v_cmp_gt_f32_e32 vcc, s15, v17
	s_nop 1
	v_cndmask_b32_e32 v17, v17, v34, vcc
	v_rsq_f32_e32 v17, v17
	s_nop 0
	v_mul_f32_e32 v34, 0x45800000, v17
	v_cndmask_b32_e32 v34, v17, v34, vcc
	v_pk_mul_f32 v[6:7], v[34:35], v[6:7] op_sel_hi:[0,1]
	v_pk_mul_f32 v[8:9], v[34:35], v[8:9] op_sel_hi:[0,1]
	v_pk_mul_f32 v[8:9], v[8:9], v[20:21]
	v_pk_mul_f32 v[6:7], v[6:7], v[18:19]
	global_store_dwordx4 v[210:211], v[6:9], off
	v_pk_mul_f32 v[18:19], v[34:35], v[22:23] op_sel_hi:[0,1]
	v_pk_mul_f32 v[20:21], v[34:35], v[24:25] op_sel_hi:[0,1]
	v_pk_mul_f32 v[6:7], v[20:21], v[212:213]
	v_pk_mul_f32 v[8:9], v[18:19], v[214:215]
	global_store_dwordx4 v[210:211], v[6:9], off offset:1024
	v_pk_mul_f32 v[18:19], v[34:35], v[26:27] op_sel_hi:[0,1]
	v_pk_mul_f32 v[20:21], v[34:35], v[28:29] op_sel_hi:[0,1]
	v_pk_mul_f32 v[6:7], v[20:21], v[216:217]
	v_pk_mul_f32 v[8:9], v[18:19], v[218:219]
	global_store_dwordx4 v[210:211], v[6:9], off offset:2048
	v_pk_mul_f32 v[18:19], v[34:35], v[30:31] op_sel_hi:[0,1]
	v_pk_mul_f32 v[20:21], v[34:35], v[32:33] op_sel_hi:[0,1]
	v_pk_mul_f32 v[6:7], v[20:21], v[220:221]
	v_pk_mul_f32 v[8:9], v[18:19], v[222:223]
	global_store_dwordx4 v[210:211], v[6:9], off offset:3072
	s_cbranch_scc0 .LBB0_1955
